# gate/up epilogue stores written through at agent scope (sc1): the streamed hidden tile no longer fills L2 with dirty lines; plus exp2 argument by one fma in the compressed-branch loops
# baseline (speedup 1.0000x reference)
; #define LAS __attribute__((address_space(3)))
; __device__ __forceinline__ float fexp(float x) { return __expf(x); }
; template <int MODE>
; __device__ __forceinline__ void softmax_block(f32x4 (&acc)[4], int base, bool ok, int t, int g4, const LAS float* lutg, SmState& st, f32x4 (&O)[4], bf16x8 (&pB)[2]) {
;     float mx = -1e30f; unsigned vm = 0u;
; #pragma unroll
;     for (int nt = 0; nt < 4; ++nt)
; #pragma unroll
;         for (int i = 0; i < 4; ++i) {
;             const int key = base + 16 * nt + 4 * g4 + i;
;             const int dist = (MODE == 0) ? t - (16 * key + 31) : t - key;
;             bool valid = dist >= 0;
;             if (MODE == 1) valid = valid && ok;
;             if (MODE == 2) valid = valid && dist < 512;
;             int dc = dist < 0 ? 0 : dist; dc = dc > 1023 ? 1023 : dc;
;             const float lg = acc[nt][i] + lutg[dc * 4];
;             acc[nt][i] = lg;
;             if (valid) { mx = fmaxf(mx, lg); vm |= 1u << (nt * 4 + i); }
;         }
;     mx = fmaxf(mx, __shfl_xor(mx, 16)); mx = fmaxf(mx, __shfl_xor(mx, 32));
;     const float mn = fmaxf(st.m, mx);
;     const float sc = fexp(st.m - mn);
;     float ls = 0.f;
; #pragma unroll
;     for (int nt = 0; nt < 4; ++nt)
; #pragma unroll
;         for (int i = 0; i < 4; ++i) { const float p = ((vm >> (nt * 4 + i)) & 1u) ? fexp(acc[nt][i] - mn) : 0.f; acc[nt][i] = p; ls += p; }
;     st.l = st.l * sc + ls; st.m = mn;
.Lc1_nokpf:
	s_waitcnt lgkmcnt(0)
	s_nop 7
	v_add_f32_e32 v228, v228, v244
	v_add_f32_e32 v229, v229, v245
	v_add_f32_e32 v230, v230, v246
	v_add_f32_e32 v231, v231, v247
	v_add_f32_e32 v232, v232, v248
	v_add_f32_e32 v233, v233, v249
	v_add_f32_e32 v234, v234, v250
	v_add_f32_e32 v235, v235, v251
	v_add_f32_e32 v236, v236, v252
	v_add_f32_e32 v237, v237, v253
	v_add_f32_e32 v238, v238, v255
	v_add_f32_e32 v239, v239, v98
	v_add_f32_e32 v240, v240, v99
	v_add_f32_e32 v241, v241, v116
	v_add_f32_e32 v242, v242, v117
	v_add_f32_e32 v243, v243, v118
	v_cndmask_b32_e64 v244, v182, v228, s[46:47]
	v_cndmask_b32_e64 v245, v182, v229, s[48:49]
	v_cndmask_b32_e64 v246, v182, v230, s[50:51]
	v_cndmask_b32_e64 v247, v182, v231, s[52:53]
	v_cndmask_b32_e64 v248, v182, v232, s[54:55]
	v_cndmask_b32_e64 v249, v182, v233, s[56:57]
	v_cndmask_b32_e64 v250, v182, v234, s[58:59]
	v_cndmask_b32_e64 v251, v182, v235, s[60:61]
	v_cndmask_b32_e64 v252, v182, v236, s[62:63]
	v_cndmask_b32_e64 v253, v182, v237, s[64:65]
	v_cndmask_b32_e64 v255, v182, v238, s[66:67]
	v_cndmask_b32_e64 v98, v182, v239, s[68:69]
	v_cndmask_b32_e64 v99, v182, v240, s[24:25]
	v_cndmask_b32_e64 v116, v182, v241, s[98:99]
	v_cndmask_b32_e64 v117, v182, v242, s[100:101]
	v_cndmask_b32_e64 v118, v182, v243, s[22:23]
	v_max3_f32 v244, v244, v245, v246
	v_max3_f32 v247, v247, v248, v249
	v_max3_f32 v250, v250, v251, v252
	v_max3_f32 v253, v253, v255, v98
	v_max3_f32 v99, v99, v116, v117
	v_max3_f32 v244, v244, v247, v250
	v_max3_f32 v253, v253, v99, v118
	v_max_f32_e32 v244, v244, v253
	v_mov_b32_e32 v120, v244
	s_nop 1
	v_permlane16_swap_b32_e32 v244, v120
	v_max_f32_e32 v244, v244, v120
	v_mov_b32_e32 v120, v244
	s_nop 1
	v_permlane32_swap_b32_e32 v244, v120
	v_max3_f32 v124, v76, v244, v120
	v_sub_f32_e32 v126, v76, v124
	v_mul_f32_e32 v120, 0xbfb8aa3b, v124
	v_mul_f32_e32 v126, 0x3fb8aa3b, v126
	v_fmamk_f32 v228, v228, 0x3fb8aa3b, v120
	v_fmamk_f32 v229, v229, 0x3fb8aa3b, v120
	v_fmamk_f32 v230, v230, 0x3fb8aa3b, v120
	v_fmamk_f32 v231, v231, 0x3fb8aa3b, v120
	v_fmamk_f32 v232, v232, 0x3fb8aa3b, v120
	v_fmamk_f32 v233, v233, 0x3fb8aa3b, v120
	v_fmamk_f32 v234, v234, 0x3fb8aa3b, v120
	v_fmamk_f32 v235, v235, 0x3fb8aa3b, v120
	v_fmamk_f32 v236, v236, 0x3fb8aa3b, v120
	v_fmamk_f32 v237, v237, 0x3fb8aa3b, v120
	v_fmamk_f32 v238, v238, 0x3fb8aa3b, v120
	v_fmamk_f32 v239, v239, 0x3fb8aa3b, v120
	v_fmamk_f32 v240, v240, 0x3fb8aa3b, v120
	v_fmamk_f32 v241, v241, 0x3fb8aa3b, v120
	v_fmamk_f32 v242, v242, 0x3fb8aa3b, v120
	v_fmamk_f32 v243, v243, 0x3fb8aa3b, v120
	v_exp_f32_e32 v126, v126
	v_exp_f32_e32 v228, v228
	v_exp_f32_e32 v229, v229
	v_exp_f32_e32 v230, v230
	v_exp_f32_e32 v231, v231
	v_exp_f32_e32 v232, v232
	v_exp_f32_e32 v233, v233
	v_exp_f32_e32 v234, v234
	v_exp_f32_e32 v235, v235
	v_exp_f32_e32 v236, v236
	v_exp_f32_e32 v237, v237
	v_exp_f32_e32 v238, v238
	v_exp_f32_e32 v239, v239
	v_exp_f32_e32 v240, v240
	v_exp_f32_e32 v241, v241
	v_exp_f32_e32 v242, v242
	v_exp_f32_e32 v243, v243
	v_mov_b32_e32 v76, v124
	v_cndmask_b32_e64 v228, 0, v228, s[46:47]
	v_cndmask_b32_e64 v229, 0, v229, s[48:49]
	v_cndmask_b32_e64 v230, 0, v230, s[50:51]
	v_cndmask_b32_e64 v231, 0, v231, s[52:53]
	v_cndmask_b32_e64 v232, 0, v232, s[54:55]
	v_cndmask_b32_e64 v233, 0, v233, s[56:57]
	v_cndmask_b32_e64 v234, 0, v234, s[58:59]
	v_cndmask_b32_e64 v235, 0, v235, s[60:61]
	v_cndmask_b32_e64 v236, 0, v236, s[62:63]
	v_cndmask_b32_e64 v237, 0, v237, s[64:65]
	v_cndmask_b32_e64 v238, 0, v238, s[66:67]
	v_cndmask_b32_e64 v239, 0, v239, s[68:69]
	v_cndmask_b32_e64 v240, 0, v240, s[24:25]
	v_cndmask_b32_e64 v241, 0, v241, s[98:99]
	v_cndmask_b32_e64 v242, 0, v242, s[100:101]
	v_cndmask_b32_e64 v243, 0, v243, s[22:23]
	v_add_f32_e32 v120, v229, v228
	v_add_f32_e32 v120, v230, v120
	v_add_f32_e32 v120, v231, v120
	v_add_f32_e32 v120, v232, v120
	v_add_f32_e32 v120, v233, v120
	v_add_f32_e32 v120, v234, v120
	v_add_f32_e32 v120, v235, v120
	v_add_f32_e32 v120, v236, v120
	v_add_f32_e32 v120, v237, v120
	v_add_f32_e32 v120, v238, v120
	v_add_f32_e32 v120, v239, v120
	v_add_f32_e32 v120, v240, v120
	v_add_f32_e32 v120, v241, v120
	v_add_f32_e32 v120, v242, v120
	v_add_f32_e32 v120, v243, v120
	v_fmac_f32_e32 v120, v8, v126
	s_cmp_eq_u32 s72, 0
	v_mov_b32_e32 v8, v120
	s_cbranch_scc0 .Lc1_loop
	v_mov_b32_e32 v74, v170
	v_mov_b32_e32 v73, v177
	v_mov_b32_e32 v77, v171
	s_branch .LBB0_900

; __device__ __forceinline__ void nsa_wave(CArgs* Ap, int l, int b, int g, int tq0, const LAS float* lut, LAS float* imp, int lane) {
;     ...
;         float lt = st.l; lt += __shfl_xor(lt, 16); lt += __shfl_xor(lt, 32);
;         const float inv = 1.f / fmaxf(lt, 1e-30f), mfin = st.m;
;         for (int cb = 0; cb < ncb; ++cb) {
;             bf16x8 kf[4][2]; load_k(kf, KC + (size_t)cb * 4096, lane);
;             bf16x8 vf[4][2]; load_v(vf, VCT + (size_t)cb * 4096, lane);
;             f32x4 acc[4];
; #pragma unroll
;             for (int nt = 0; nt < 4; ++nt) acc[nt] = (f32x4){0.f, 0.f, 0.f, 0.f};
;             qk_acc(acc, kf, qB);
.LBB0_900:
	v_lshlrev_b32_e32 v207, 6, v20
	v_cmp_lt_i32_e32 vcc, v21, v77
	v_mov_b32_e32 v19, 0
	v_xor_b32_e32 v79, 1, v74
	v_cndmask_b32_e32 v9, v74, v21, vcc
	v_lshlrev_b32_e32 v209, 2, v9
	ds_bpermute_b32 v9, v209, v8
	v_cmp_lt_i32_e32 vcc, v22, v77
	v_xor_b32_e32 v78, 2, v74
	v_cmp_lt_i32_e64 s[48:49], v79, v77
	v_cndmask_b32_e32 v10, v74, v22, vcc
	v_lshlrev_b32_e32 v208, 2, v10
	s_waitcnt lgkmcnt(0)
	v_add_f32_e32 v24, v8, v9
	ds_bpermute_b32 v25, v208, v24
	s_andn2_b64 vcc, exec, s[96:97]
	v_cmp_lt_i32_e64 s[46:47], v78, v77
	v_mov_b32_e32 v18, v19
	v_mov_b32_e32 v17, v19
	v_mov_b32_e32 v16, v19
	v_mov_b32_e32 v11, v19
	v_mov_b32_e32 v10, v19
	v_mov_b32_e32 v9, v19
	v_mov_b32_e32 v8, v19
	v_mov_b32_e32 v15, v19
	v_mov_b32_e32 v14, v19
	v_mov_b32_e32 v13, v19
	v_mov_b32_e32 v12, v19
	v_mov_b32_e32 v23, v19
	v_mov_b32_e32 v22, v19
	v_mov_b32_e32 v21, v19
	v_mov_b32_e32 v20, v19
	s_cbranch_vccnz .LBB0_943
	s_waitcnt lgkmcnt(0)
	v_add_f32_e32 v8, v24, v25
	v_max_f32_e32 v8, 0xda24260, v8
	v_div_scale_f32 v9, s[0:1], v8, v8, 1.0
	v_rcp_f32_e32 v10, v9
	v_div_scale_f32 v11, vcc, 1.0, v8, 1.0
	s_add_i32 s0, s20, s17
	v_fma_f32 v12, -v9, v10, 1.0
	v_fmac_f32_e32 v10, v12, v10
	v_mul_f32_e32 v12, v11, v10
	v_fma_f32 v13, -v9, v12, v11
	v_fmac_f32_e32 v12, v13, v10
	v_fma_f32 v9, -v9, v12, v11
	v_div_fmas_f32 v9, v9, v10, v12
	v_div_fixup_f32 v80, v9, v8, 1.0
	s_lshl_b32 s21, s21, 8
	s_ashr_i32 s1, s0, 31
	s_addk_i32 s21, 0x100
	s_lshl_b64 s[0:1], s[0:1], 16
	s_add_u32 s0, s15, s0
	s_addc_u32 s1, s16, s1
	s_mov_b32 s22, 0
	v_mov_b32_e32 v8, 0
	v_mov_b32_e32 v9, 0
	v_mov_b32_e32 v10, 0
	v_mov_b32_e32 v11, 0
	v_mov_b32_e32 v12, 0
	v_mov_b32_e32 v13, 0
	v_mov_b32_e32 v14, 0
	v_mov_b32_e32 v15, 0
	v_mov_b32_e32 v16, 0
	v_mov_b32_e32 v17, 0
	v_mov_b32_e32 v18, 0
	v_mov_b32_e32 v19, 0
	v_mov_b32_e32 v20, 0
	v_mov_b32_e32 v21, 0
	v_mov_b32_e32 v22, 0
	v_mov_b32_e32 v23, 0
	v_lshl_add_u64 v[126:127], s[0:1], 0, v[84:85]
	s_mov_b32 s23, 0x2a201000
	v_add_co_u32_e32 v120, vcc, s23, v126
	s_mov_b32 s23, 0x2a601000
	s_nop 0
	v_addc_co_u32_e32 v121, vcc, 0, v127, vcc
	v_add_co_u32_e32 v122, vcc, s23, v126
	v_add_u32_e32 v124, 0x10000, v203
	s_mov_b64 s[0:1], 0x2000
	v_addc_co_u32_e32 v123, vcc, 0, v127, vcc
	global_load_dwordx4 v[24:27], v[120:121], off offset:-4096
	global_load_dwordx4 v[28:31], v[120:121], off offset:-3072
	global_load_dwordx4 v[32:35], v[120:121], off offset:-2048
	global_load_dwordx4 v[36:39], v[120:121], off offset:-1024
	global_load_dwordx4 v[40:43], v[120:121], off offset:0
	global_load_dwordx4 v[44:47], v[120:121], off offset:1024
	global_load_dwordx4 v[48:51], v[120:121], off offset:2048
	global_load_dwordx4 v[52:55], v[120:121], off offset:3072
	global_load_dwordx4 v[56:59], v[122:123], off offset:-4096
	global_load_dwordx4 v[60:63], v[122:123], off offset:-3072
	global_load_dwordx4 v[64:67], v[122:123], off offset:-2048
	global_load_dwordx4 v[68:71], v[122:123], off offset:-1024
	global_load_dwordx4 v[100:103], v[122:123], off offset:0
	global_load_dwordx4 v[104:107], v[122:123], off offset:1024
	global_load_dwordx4 v[108:111], v[122:123], off offset:2048
	global_load_dwordx4 v[112:115], v[122:123], off offset:3072
	v_mul_f32_e32 v126, 0xbfb8aa3b, v76

; #define LAS __attribute__((address_space(3)))
; __device__ __forceinline__ unsigned pk2(float lo, float hi) { return pg8::cvt_pk_bf16(lo, hi); }
; __device__ __forceinline__ float fexp(float x) { return __expf(x); }
; __device__ __forceinline__ void nsa_wave(CArgs* Ap, int l, int b, int g, int tq0, const LAS float* lut, LAS float* imp, int lane) {
;     ...
;             for (int nt = 0; nt < 4; ++nt) {
;                 f32x4 pi4;
; #pragma unroll
;                 for (int i = 0; i < 4; ++i) {
;                     const int key = cb * 64 + 16 * nt + 4 * g4 + i; const int dist = t - (16 * key + 31);
;                     int dc = dist < 0 ? 0 : dist; dc = dc > 1023 ? 1023 : dc;
;                     const float lg = acc[nt][i] + lutg[dc * 4];
;                     float p = (dist >= 0) ? fexp(lg - mfin) * inv : 0.f;
;                     acc[nt][i] = p;
;                     p += __shfl_xor(p, 1); p += __shfl_xor(p, 2);
;                     pi4[i] = p;
;                 }
;                 if (r == 0) *(LAS f32x4*)(imp + qi * 512 + cb * 64 + 16 * nt + 4 * g4) = pi4;
;             }
; #pragma unroll
;             for (int hh = 0; hh < 2; ++hh) { u32x4 w; w.x = pk2(acc[2 * hh][0], acc[2 * hh][1]); w.y = pk2(acc[2 * hh][2], acc[2 * hh][3]); w.z = pk2(acc[2 * hh + 1][0], acc[2 * hh + 1][1]); w.w = pk2(acc[2 * hh + 1][2], acc[2 * hh + 1][3]);
;                 pB[hh] = __builtin_bit_cast(bf16x8, w); }
;             pv_acc(outacc, vf, pB);
.Lc2_nokpf:
	s_waitcnt lgkmcnt(0)
	s_nop 7
	v_add_f32_e32 v244, v228, v244
	v_add_f32_e32 v245, v229, v245
	v_add_f32_e32 v246, v230, v246
	v_add_f32_e32 v247, v231, v247
	v_add_f32_e32 v248, v232, v248
	v_add_f32_e32 v249, v233, v249
	v_add_f32_e32 v250, v234, v250
	v_add_f32_e32 v251, v235, v251
	v_add_f32_e32 v252, v236, v252
	v_add_f32_e32 v253, v237, v253
	v_add_f32_e32 v255, v238, v255
	v_add_f32_e32 v98, v239, v98
	v_add_f32_e32 v99, v240, v99
	v_add_f32_e32 v116, v241, v116
	v_add_f32_e32 v117, v242, v117
	v_add_f32_e32 v118, v243, v118
	v_fmamk_f32 v244, v244, 0x3fb8aa3b, v126
	v_fmamk_f32 v245, v245, 0x3fb8aa3b, v126
	v_fmamk_f32 v246, v246, 0x3fb8aa3b, v126
	v_fmamk_f32 v247, v247, 0x3fb8aa3b, v126
	v_fmamk_f32 v248, v248, 0x3fb8aa3b, v126
	v_fmamk_f32 v249, v249, 0x3fb8aa3b, v126
	v_fmamk_f32 v250, v250, 0x3fb8aa3b, v126
	v_fmamk_f32 v251, v251, 0x3fb8aa3b, v126
	v_fmamk_f32 v252, v252, 0x3fb8aa3b, v126
	v_fmamk_f32 v253, v253, 0x3fb8aa3b, v126
	v_fmamk_f32 v255, v255, 0x3fb8aa3b, v126
	v_fmamk_f32 v98, v98, 0x3fb8aa3b, v126
	v_fmamk_f32 v99, v99, 0x3fb8aa3b, v126
	v_fmamk_f32 v116, v116, 0x3fb8aa3b, v126
	v_fmamk_f32 v117, v117, 0x3fb8aa3b, v126
	v_fmamk_f32 v118, v118, 0x3fb8aa3b, v126
	v_exp_f32_e32 v244, v244
	v_exp_f32_e32 v245, v245
	v_exp_f32_e32 v246, v246
	v_exp_f32_e32 v247, v247
	v_exp_f32_e32 v248, v248
	v_exp_f32_e32 v249, v249
	v_exp_f32_e32 v250, v250
	v_exp_f32_e32 v251, v251
	v_exp_f32_e32 v252, v252
	v_exp_f32_e32 v253, v253
	v_exp_f32_e32 v255, v255
	v_exp_f32_e32 v98, v98
	v_exp_f32_e32 v99, v99
	v_exp_f32_e32 v116, v116
	v_exp_f32_e32 v117, v117
	v_exp_f32_e32 v118, v118
	v_mul_f32_e32 v244, v80, v244
	v_mul_f32_e32 v245, v80, v245
	v_mul_f32_e32 v246, v80, v246
	v_mul_f32_e32 v247, v80, v247
	v_mul_f32_e32 v248, v80, v248
	v_mul_f32_e32 v249, v80, v249
	v_mul_f32_e32 v250, v80, v250
	v_mul_f32_e32 v251, v80, v251
	v_mul_f32_e32 v252, v80, v252
	v_mul_f32_e32 v253, v80, v253
	v_mul_f32_e32 v255, v80, v255
	v_mul_f32_e32 v98, v80, v98
	v_mul_f32_e32 v99, v80, v99
	v_mul_f32_e32 v116, v80, v116
	v_mul_f32_e32 v117, v80, v117
	v_mul_f32_e32 v118, v80, v118
	v_cndmask_b32_e64 v244, 0, v244, s[46:47]
	v_cndmask_b32_e64 v245, 0, v245, s[48:49]
	v_cndmask_b32_e64 v246, 0, v246, s[50:51]
	v_cndmask_b32_e64 v247, 0, v247, s[52:53]
	v_cndmask_b32_e64 v248, 0, v248, s[54:55]
	v_cndmask_b32_e64 v249, 0, v249, s[56:57]
	v_cndmask_b32_e64 v250, 0, v250, s[58:59]
	v_cndmask_b32_e64 v251, 0, v251, s[60:61]
	v_cndmask_b32_e64 v252, 0, v252, s[62:63]
	v_cndmask_b32_e64 v253, 0, v253, s[64:65]
	v_cndmask_b32_e64 v255, 0, v255, s[66:67]
	v_cndmask_b32_e64 v98, 0, v98, s[68:69]
	v_cndmask_b32_e64 v99, 0, v99, s[96:97]
	v_cndmask_b32_e64 v116, 0, v116, s[98:99]
	v_cndmask_b32_e64 v117, 0, v117, s[100:101]
	v_cndmask_b32_e64 v118, 0, v118, s[76:77]
	v_add_f32_dpp v228, v244, v244 quad_perm:[1,0,3,2] row_mask:0xf bank_mask:0xf
	v_add_f32_dpp v229, v245, v245 quad_perm:[1,0,3,2] row_mask:0xf bank_mask:0xf
	v_add_f32_dpp v230, v246, v246 quad_perm:[1,0,3,2] row_mask:0xf bank_mask:0xf
	v_add_f32_dpp v231, v247, v247 quad_perm:[1,0,3,2] row_mask:0xf bank_mask:0xf
	v_add_f32_dpp v232, v248, v248 quad_perm:[1,0,3,2] row_mask:0xf bank_mask:0xf
	v_add_f32_dpp v233, v249, v249 quad_perm:[1,0,3,2] row_mask:0xf bank_mask:0xf
	v_add_f32_dpp v234, v250, v250 quad_perm:[1,0,3,2] row_mask:0xf bank_mask:0xf
	v_add_f32_dpp v235, v251, v251 quad_perm:[1,0,3,2] row_mask:0xf bank_mask:0xf
	v_add_f32_dpp v236, v252, v252 quad_perm:[1,0,3,2] row_mask:0xf bank_mask:0xf
	v_add_f32_dpp v237, v253, v253 quad_perm:[1,0,3,2] row_mask:0xf bank_mask:0xf
	v_add_f32_dpp v238, v255, v255 quad_perm:[1,0,3,2] row_mask:0xf bank_mask:0xf
	v_add_f32_dpp v239, v98, v98 quad_perm:[1,0,3,2] row_mask:0xf bank_mask:0xf
	v_add_f32_dpp v240, v99, v99 quad_perm:[1,0,3,2] row_mask:0xf bank_mask:0xf
	v_add_f32_dpp v241, v116, v116 quad_perm:[1,0,3,2] row_mask:0xf bank_mask:0xf
	v_add_f32_dpp v242, v117, v117 quad_perm:[1,0,3,2] row_mask:0xf bank_mask:0xf
	v_add_f32_dpp v243, v118, v118 quad_perm:[1,0,3,2] row_mask:0xf bank_mask:0xf
	v_add_f32_dpp v228, v228, v228 quad_perm:[2,3,0,1] row_mask:0xf bank_mask:0xf
	v_add_f32_dpp v229, v229, v229 quad_perm:[2,3,0,1] row_mask:0xf bank_mask:0xf
	v_add_f32_dpp v230, v230, v230 quad_perm:[2,3,0,1] row_mask:0xf bank_mask:0xf
	v_add_f32_dpp v231, v231, v231 quad_perm:[2,3,0,1] row_mask:0xf bank_mask:0xf
	v_add_f32_dpp v232, v232, v232 quad_perm:[2,3,0,1] row_mask:0xf bank_mask:0xf
	v_add_f32_dpp v233, v233, v233 quad_perm:[2,3,0,1] row_mask:0xf bank_mask:0xf
	v_add_f32_dpp v234, v234, v234 quad_perm:[2,3,0,1] row_mask:0xf bank_mask:0xf
	v_add_f32_dpp v235, v235, v235 quad_perm:[2,3,0,1] row_mask:0xf bank_mask:0xf
	v_add_f32_dpp v236, v236, v236 quad_perm:[2,3,0,1] row_mask:0xf bank_mask:0xf
	v_add_f32_dpp v237, v237, v237 quad_perm:[2,3,0,1] row_mask:0xf bank_mask:0xf
	v_add_f32_dpp v238, v238, v238 quad_perm:[2,3,0,1] row_mask:0xf bank_mask:0xf
	v_add_f32_dpp v239, v239, v239 quad_perm:[2,3,0,1] row_mask:0xf bank_mask:0xf
	v_add_f32_dpp v240, v240, v240 quad_perm:[2,3,0,1] row_mask:0xf bank_mask:0xf
	v_add_f32_dpp v241, v241, v241 quad_perm:[2,3,0,1] row_mask:0xf bank_mask:0xf
	v_add_f32_dpp v242, v242, v242 quad_perm:[2,3,0,1] row_mask:0xf bank_mask:0xf
	v_add_f32_dpp v243, v243, v243 quad_perm:[2,3,0,1] row_mask:0xf bank_mask:0xf
	s_mov_b64 exec, s[2:3]
	ds_write_b128 v124, v[228:231]
	ds_write_b128 v124, v[232:235] offset:64
	ds_write_b128 v124, v[236:239] offset:128
	ds_write_b128 v124, v[240:243] offset:192
	s_mov_b64 exec, -1
	v_add_u32_e32 v124, 0x100, v124
	v_cvt_pk_bf16_f32 v244, v244, v245
	v_cvt_pk_bf16_f32 v245, v246, v247
	v_cvt_pk_bf16_f32 v246, v248, v249
	v_cvt_pk_bf16_f32 v247, v250, v251
	v_cvt_pk_bf16_f32 v248, v252, v253
	v_cvt_pk_bf16_f32 v249, v255, v98
	v_cvt_pk_bf16_f32 v250, v99, v116
	v_cvt_pk_bf16_f32 v251, v117, v118
	s_cmp_lg_u32 s22, s21
	s_cbranch_scc0 .Lc2_last
	s_waitcnt vmcnt(8)
	v_mfma_f32_16x16x32_bf16 v[16:19], v[56:59], v[244:247], v[16:19]
	v_mfma_f32_16x16x32_bf16 v[20:23], v[64:67], v[244:247], v[20:23]
	v_mfma_f32_16x16x32_bf16 v[12:15], v[100:103], v[244:247], v[12:15]
	v_mfma_f32_16x16x32_bf16 v[8:11], v[108:111], v[244:247], v[8:11]
	v_mfma_f32_16x16x32_bf16 v[16:19], v[60:63], v[248:251], v[16:19]
	v_mfma_f32_16x16x32_bf16 v[20:23], v[68:71], v[248:251], v[20:23]
	v_mfma_f32_16x16x32_bf16 v[12:15], v[104:107], v[248:251], v[12:15]
	v_mfma_f32_16x16x32_bf16 v[8:11], v[112:115], v[248:251], v[8:11]
	global_load_dwordx4 v[56:59], v[122:123], off offset:-4096
	global_load_dwordx4 v[60:63], v[122:123], off offset:-3072
	global_load_dwordx4 v[64:67], v[122:123], off offset:-2048
	global_load_dwordx4 v[68:71], v[122:123], off offset:-1024
	global_load_dwordx4 v[100:103], v[122:123], off offset:0
	global_load_dwordx4 v[104:107], v[122:123], off offset:1024
	global_load_dwordx4 v[108:111], v[122:123], off offset:2048
	global_load_dwordx4 v[112:115], v[122:123], off offset:3072
	s_branch .Lc2_loop

; __device__ __forceinline__ unsigned pk2(float lo, float hi) { return pg8::cvt_pk_bf16(lo, hi); }
; __device__ __forceinline__ float sigmoidf_(float x) { return __builtin_amdgcn_rcpf(1.f + fexp(-x)); }
;     __device__ __forceinline__ float rs(int r, int fq) const { return (r >> 8) == tab_pm ? tab[r & 255] : row_rstd(rowsq, r, fq); }
;     __device__ __forceinline__ float rs(int r, int fq) const { return (r >> 8) == tab_pm ? tab[r & 255] : row_rstd(rowsq, r, fq); }
; __device__ __forceinline__ float row_rstd(const float* part, int r, int fq) {
;     float s = 0.f;
; #pragma unroll
;     for (int k = 0; k < 8; ++k) s += part[(size_t)(fq * 8 + k) * MTOK + r];
;     s += __shfl_xor(s, 16); s += __shfl_xor(s, 32);
;     return rsqrtf(s * (1.f / DM) + EPS);
; }
;     __device__ __forceinline__ void operator()(const f32x4 (&acc)[2][2][4][2], const pg8::Unit& u, int wr, int wc, int fr, int fq) const {
;         const int row0 = u.pm * 256 + wr * 64 + fr;
; #pragma unroll
;         for (int ai = 0; ai < 2; ++ai)
; #pragma unroll
;             for (int m = 0; m < 4; ++m) {
;                 const int r = row0 + ai * 128 + m * 16;
;                 const float rstd = rs(r, fq);
;                 float o[2][4];
; #pragma unroll
;                 for (int bj = 0; bj < 2; ++bj) {
;                     const f32x4 gv = acc[ai][bj][m][0] * rstd, uv = acc[ai][bj][m][1] * rstd;
; #pragma unroll
;                     for (int i = 0; i < 4; ++i) o[bj][i] = gv[i] * sigmoidf_(gv[i]) * uv[i];
;                 }
;                 const int j0 = u.pn * 128 + wc * 32 + 8 * fq;
;                 u32x4 w; w.x = pk2(o[0][0], o[0][1]); w.y = pk2(o[0][2], o[0][3]); w.z = pk2(o[1][0], o[1][1]); w.w = pk2(o[1][2], o[1][3]);
;                 *(u32x4*)(HID + (size_t)r * DFF + j0) = w;
;             }
;     }
.LBB0_1418:
	s_waitcnt lgkmcnt(0)
	v_pk_mul_f32 v[124:125], v[124:125], v[140:141] op_sel_hi:[1,0]
	v_pk_mul_f32 v[126:127], v[126:127], v[140:141] op_sel_hi:[1,0]
	v_mul_f32_e32 v137, 0xbfb8aa3b, v124
	v_exp_f32_e32 v150, v137
	v_mul_f32_e32 v137, 0xbfb8aa3b, v125
	v_mul_f32_e32 v153, 0xbfb8aa3b, v126
	v_exp_f32_e32 v151, v137
	v_exp_f32_e32 v153, v153
	v_mul_f32_e32 v154, 0xbfb8aa3b, v127
	v_exp_f32_e32 v155, v154
	v_add_f32_e32 v150, 1.0, v150
	v_add_f32_e32 v151, 1.0, v151
	v_add_f32_e32 v153, 1.0, v153
	v_rcp_f32_e32 v150, v150
	v_rcp_f32_e32 v151, v151
	v_rcp_f32_e32 v154, v153
	v_add_f32_e32 v153, 1.0, v155
	v_rcp_f32_e32 v155, v153
	v_pk_mul_f32 v[124:125], v[124:125], v[150:151]
	v_pk_mul_f32 v[120:121], v[120:121], v[140:141] op_sel_hi:[1,0]
	v_pk_mul_f32 v[116:117], v[116:117], v[140:141] op_sel_hi:[1,0]
	v_pk_mul_f32 v[120:121], v[120:121], v[124:125]
	v_pk_mul_f32 v[124:125], v[126:127], v[154:155]
	v_mul_f32_e32 v126, 0xbfb8aa3b, v116
	v_mul_f32_e32 v127, 0xbfb8aa3b, v117
	v_exp_f32_e32 v126, v126
	v_exp_f32_e32 v127, v127
	v_pk_mul_f32 v[122:123], v[122:123], v[140:141] op_sel_hi:[1,0]
	v_pk_mul_f32 v[118:119], v[118:119], v[140:141] op_sel_hi:[1,0]
	v_pk_mul_f32 v[122:123], v[122:123], v[124:125]
	v_add_f32_e32 v124, 1.0, v126
	v_add_f32_e32 v125, 1.0, v127
	v_mul_f32_e32 v126, 0xbfb8aa3b, v118
	v_mul_f32_e32 v127, 0xbfb8aa3b, v119
	v_exp_f32_e32 v126, v126
	v_exp_f32_e32 v127, v127
	v_rcp_f32_e32 v124, v124
	v_rcp_f32_e32 v125, v125
	v_add_f32_e32 v126, 1.0, v126
	v_add_f32_e32 v127, 1.0, v127
	v_rcp_f32_e32 v126, v126
	v_rcp_f32_e32 v127, v127
	v_pk_mul_f32 v[116:117], v[116:117], v[124:125]
	v_pk_mul_f32 v[112:113], v[112:113], v[140:141] op_sel_hi:[1,0]
	v_pk_mul_f32 v[114:115], v[114:115], v[140:141] op_sel_hi:[1,0]
	v_pk_mul_f32 v[116:117], v[112:113], v[116:117]
	v_pk_mul_f32 v[112:113], v[118:119], v[126:127]
	v_lshl_or_b32 v136, s0, 7, v143
	v_pk_mul_f32 v[118:119], v[114:115], v[112:113]
	v_cvt_pk_bf16_f32 v114, v116, v117
	v_mov_b64_e32 v[116:117], s[8:9]
	v_mad_u64_u32 v[116:117], s[0:1], v138, s90, v[116:117]
	v_cvt_pk_bf16_f32 v115, v118, v119
	v_mov_b32_e32 v118, v117
	v_mad_u64_u32 v[118:119], s[0:1], v139, s90, v[118:119]
	v_ashrrev_i32_e32 v137, 31, v136
	v_mov_b32_e32 v117, v118
	v_cvt_pk_bf16_f32 v112, v120, v121
	v_cvt_pk_bf16_f32 v113, v122, v123
	v_lshl_add_u64 v[116:117], v[136:137], 1, v[116:117]
	global_store_dwordx4 v[116:117], v[112:115], off sc1
	s_mov_b64 s[0:1], -1
	s_andn2_b64 vcc, exec, s[20:21]
	v_or_b32_e32 v112, 16, v138
	v_cndmask_b32_e64 v113, 0, 1, s[20:21]
	v_cmp_ne_u32_e64 s[4:5], 1, v113
	v_ashrrev_i32_e32 v113, 31, v112
	s_cbranch_vccnz .LBB0_1420
	v_lshl_add_u64 v[114:115], v[138:139], 2, v[130:131]
	v_add_co_u32_e32 v116, vcc, 0x10000, v114
	s_mov_b64 s[0:1], 0
	s_nop 0
	v_addc_co_u32_e32 v117, vcc, 0, v115, vcc
	v_add_co_u32_e32 v118, vcc, 0x20000, v114
	s_nop 1
	v_addc_co_u32_e32 v119, vcc, 0, v115, vcc
	v_add_co_u32_e32 v120, vcc, 0x30000, v114
	s_nop 1
	v_addc_co_u32_e32 v121, vcc, 0, v115, vcc
	v_add_co_u32_e32 v122, vcc, 0x40000, v114
	s_nop 1
	v_addc_co_u32_e32 v123, vcc, 0, v115, vcc
	v_add_co_u32_e32 v124, vcc, 0x50000, v114
	s_nop 1
	v_addc_co_u32_e32 v125, vcc, 0, v115, vcc
	v_add_co_u32_e32 v126, vcc, 0x60000, v114
	s_nop 1
	v_addc_co_u32_e32 v127, vcc, 0, v115, vcc
	v_add_co_u32_e32 v150, vcc, 0x70000, v114
	s_nop 1
	v_addc_co_u32_e32 v151, vcc, 0, v115, vcc
	v_xor_b32_e32 v122, 16, v170
	v_cmp_lt_i32_e32 vcc, v122, v171
	s_waitcnt vmcnt(25)
	v_mov_b32_e32 v114, v236
	v_mov_b32_e32 v115, v237
	v_mov_b32_e32 v116, v238
	v_mov_b32_e32 v117, v239
	v_mov_b32_e32 v118, v240
	v_mov_b32_e32 v119, v241
	v_mov_b32_e32 v120, v242
	v_mov_b32_e32 v121, v243
	global_load_dword v236, v[194:195], off offset:576
	global_load_dword v237, v[196:197], off offset:576
	global_load_dword v238, v[198:199], off offset:576
	global_load_dword v239, v[200:201], off offset:576
	global_load_dword v240, v[202:203], off offset:576
	global_load_dword v241, v[204:205], off offset:576
	global_load_dword v242, v[206:207], off offset:576
	global_load_dword v243, v[208:209], off offset:576
	v_add_f32_e32 v114, 0, v114
	v_add_f32_e32 v114, v114, v115
	v_add_f32_e32 v114, v114, v116
	v_add_f32_e32 v114, v114, v117
	v_add_f32_e32 v114, v114, v118
	v_add_f32_e32 v114, v114, v119
	v_cndmask_b32_e32 v122, v170, v122, vcc
	v_add_f32_e32 v114, v114, v120
	v_lshlrev_b32_e32 v122, 2, v122
	v_add_f32_e32 v114, v114, v121
	ds_bpermute_b32 v115, v122, v114
	v_xor_b32_e32 v116, 32, v170
	v_cmp_lt_i32_e32 vcc, v116, v171
	s_waitcnt lgkmcnt(0)
	v_add_f32_e32 v114, v114, v115
	v_cndmask_b32_e32 v116, v170, v116, vcc
	v_lshlrev_b32_e32 v116, 2, v116
	ds_bpermute_b32 v115, v116, v114
	s_waitcnt lgkmcnt(0)
	v_add_f32_e32 v114, v114, v115
	v_fmamk_f32 v114, v114, 0x3a000000, v167
	v_mul_f32_e32 v115, 0x4b800000, v114
	v_cmp_gt_f32_e32 vcc, s33, v114
	s_nop 1
	v_cndmask_b32_e32 v114, v114, v115, vcc
	v_rsq_f32_e32 v114, v114
	s_nop 0
	v_mul_f32_e32 v115, 0x45800000, v114
	v_cndmask_b32_e32 v114, v114, v115, vcc

; __device__ __forceinline__ unsigned pk2(float lo, float hi) { return pg8::cvt_pk_bf16(lo, hi); }
; __device__ __forceinline__ float sigmoidf_(float x) { return __builtin_amdgcn_rcpf(1.f + fexp(-x)); }
;     __device__ __forceinline__ float rs(int r, int fq) const { return (r >> 8) == tab_pm ? tab[r & 255] : row_rstd(rowsq, r, fq); }
;     __device__ __forceinline__ float rs(int r, int fq) const { return (r >> 8) == tab_pm ? tab[r & 255] : row_rstd(rowsq, r, fq); }
; __device__ __forceinline__ float row_rstd(const float* part, int r, int fq) {
;     float s = 0.f;
; #pragma unroll
;     for (int k = 0; k < 8; ++k) s += part[(size_t)(fq * 8 + k) * MTOK + r];
;     s += __shfl_xor(s, 16); s += __shfl_xor(s, 32);
;     return rsqrtf(s * (1.f / DM) + EPS);
; }
;     __device__ __forceinline__ void operator()(const f32x4 (&acc)[2][2][4][2], const pg8::Unit& u, int wr, int wc, int fr, int fq) const {
;         const int row0 = u.pm * 256 + wr * 64 + fr;
; #pragma unroll
;         for (int ai = 0; ai < 2; ++ai)
; #pragma unroll
;             for (int m = 0; m < 4; ++m) {
;                 const int r = row0 + ai * 128 + m * 16;
;                 const float rstd = rs(r, fq);
;                 float o[2][4];
; #pragma unroll
;                 for (int bj = 0; bj < 2; ++bj) {
;                     const f32x4 gv = acc[ai][bj][m][0] * rstd, uv = acc[ai][bj][m][1] * rstd;
; #pragma unroll
;                     for (int i = 0; i < 4; ++i) o[bj][i] = gv[i] * sigmoidf_(gv[i]) * uv[i];
;                 }
;                 const int j0 = u.pn * 128 + wc * 32 + 8 * fq;
;                 u32x4 w; w.x = pk2(o[0][0], o[0][1]); w.y = pk2(o[0][2], o[0][3]); w.z = pk2(o[1][0], o[1][1]); w.w = pk2(o[1][2], o[1][3]);
;                 *(u32x4*)(HID + (size_t)r * DFF + j0) = w;
;             }
;     }
.LBB0_1422:
	s_waitcnt lgkmcnt(0)
	v_pk_mul_f32 v[108:109], v[108:109], v[114:115] op_sel_hi:[1,0]
	s_and_b64 vcc, exec, s[4:5]
	v_mul_f32_e32 v115, 0xbfb8aa3b, v108
	v_exp_f32_e32 v115, v115
	v_mul_f32_e32 v116, 0xbfb8aa3b, v109
	v_exp_f32_e32 v116, v116
	v_add_f32_e32 v115, 1.0, v115
	v_pk_mul_f32 v[110:111], v[110:111], v[114:115] op_sel_hi:[1,0]
	v_add_f32_e32 v117, 1.0, v116
	v_rcp_f32_e32 v116, v115
	v_mul_f32_e32 v115, 0xbfb8aa3b, v110
	v_exp_f32_e32 v115, v115
	v_mul_f32_e32 v118, 0xbfb8aa3b, v111
	v_exp_f32_e32 v119, v118
	v_rcp_f32_e32 v117, v117
	v_add_f32_e32 v115, 1.0, v115
	v_rcp_f32_e32 v118, v115
	v_add_f32_e32 v115, 1.0, v119
	v_rcp_f32_e32 v119, v115
	v_pk_mul_f32 v[108:109], v[108:109], v[116:117]
	v_pk_mul_f32 v[104:105], v[104:105], v[114:115] op_sel_hi:[1,0]
	v_pk_mul_f32 v[100:101], v[100:101], v[114:115] op_sel_hi:[1,0]
	v_pk_mul_f32 v[104:105], v[104:105], v[108:109]
	v_pk_mul_f32 v[108:109], v[110:111], v[118:119]
	v_mul_f32_e32 v110, 0xbfb8aa3b, v100
	v_mul_f32_e32 v111, 0xbfb8aa3b, v101
	v_exp_f32_e32 v110, v110
	v_exp_f32_e32 v111, v111
	v_pk_mul_f32 v[106:107], v[106:107], v[114:115] op_sel_hi:[1,0]
	v_pk_mul_f32 v[102:103], v[102:103], v[114:115] op_sel_hi:[1,0]
	v_pk_mul_f32 v[106:107], v[106:107], v[108:109]
	v_add_f32_e32 v108, 1.0, v110
	v_add_f32_e32 v109, 1.0, v111
	v_mul_f32_e32 v110, 0xbfb8aa3b, v102
	v_mul_f32_e32 v111, 0xbfb8aa3b, v103
	v_exp_f32_e32 v110, v110
	v_exp_f32_e32 v111, v111
	v_rcp_f32_e32 v108, v108
	v_rcp_f32_e32 v109, v109
	v_add_f32_e32 v110, 1.0, v110
	v_add_f32_e32 v111, 1.0, v111
	v_rcp_f32_e32 v110, v110
	v_rcp_f32_e32 v111, v111
	v_pk_mul_f32 v[100:101], v[100:101], v[108:109]
	v_pk_mul_f32 v[96:97], v[96:97], v[114:115] op_sel_hi:[1,0]
	v_pk_mul_f32 v[98:99], v[98:99], v[114:115] op_sel_hi:[1,0]
	v_pk_mul_f32 v[100:101], v[96:97], v[100:101]
	v_pk_mul_f32 v[96:97], v[102:103], v[110:111]
	s_nop 0
	v_pk_mul_f32 v[102:103], v[98:99], v[96:97]
	v_cvt_pk_bf16_f32 v98, v100, v101
	v_mov_b64_e32 v[100:101], s[8:9]
	v_mad_u64_u32 v[100:101], s[0:1], v112, s90, v[100:101]
	v_cvt_pk_bf16_f32 v99, v102, v103
	v_mov_b32_e32 v102, v101
	v_mad_u64_u32 v[102:103], s[0:1], v113, s90, v[102:103]
	v_mov_b32_e32 v101, v102
	v_cvt_pk_bf16_f32 v96, v104, v105
	v_cvt_pk_bf16_f32 v97, v106, v107
	v_lshl_add_u64 v[100:101], v[136:137], 1, v[100:101]
	global_store_dwordx4 v[100:101], v[96:99], off sc1
	s_mov_b64 s[0:1], -1
	s_nop 0
	v_or_b32_e32 v96, 32, v138
	v_ashrrev_i32_e32 v97, 31, v96
	s_cbranch_vccnz .LBB0_1424
	v_lshl_add_u64 v[98:99], v[138:139], 2, v[130:131]
	v_add_co_u32_e32 v100, vcc, 0x10000, v98
	s_mov_b64 s[0:1], 0
	s_nop 0
	v_addc_co_u32_e32 v101, vcc, 0, v99, vcc
	v_add_co_u32_e32 v102, vcc, 0x20000, v98
	s_nop 1
	v_addc_co_u32_e32 v103, vcc, 0, v99, vcc
	v_add_co_u32_e32 v104, vcc, 0x30000, v98
	s_nop 1
	v_addc_co_u32_e32 v105, vcc, 0, v99, vcc
	v_add_co_u32_e32 v106, vcc, 0x40000, v98
	s_nop 1
	v_addc_co_u32_e32 v107, vcc, 0, v99, vcc
	v_add_co_u32_e32 v108, vcc, 0x50000, v98
	s_nop 1
	v_addc_co_u32_e32 v109, vcc, 0, v99, vcc
	v_add_co_u32_e32 v110, vcc, 0x60000, v98
	s_nop 1
	v_addc_co_u32_e32 v111, vcc, 0, v99, vcc
	v_add_co_u32_e32 v112, vcc, 0x70000, v98
	s_nop 1
	v_addc_co_u32_e32 v113, vcc, 0, v99, vcc
	v_xor_b32_e32 v106, 16, v170
	v_cmp_lt_i32_e32 vcc, v106, v171
	s_waitcnt vmcnt(26)
	v_mov_b32_e32 v98, v244
	v_mov_b32_e32 v99, v245
	v_mov_b32_e32 v100, v246
	v_mov_b32_e32 v101, v247
	v_mov_b32_e32 v102, v248
	v_mov_b32_e32 v103, v249
	v_mov_b32_e32 v104, v250
	v_mov_b32_e32 v105, v251
	global_load_dword v244, v[194:195], off offset:640
	global_load_dword v245, v[196:197], off offset:640
	global_load_dword v246, v[198:199], off offset:640
	global_load_dword v247, v[200:201], off offset:640
	global_load_dword v248, v[202:203], off offset:640
	global_load_dword v249, v[204:205], off offset:640
	global_load_dword v250, v[206:207], off offset:640
	global_load_dword v251, v[208:209], off offset:640
	v_add_f32_e32 v98, 0, v98
	v_add_f32_e32 v98, v98, v99
	v_add_f32_e32 v98, v98, v100
	v_add_f32_e32 v98, v98, v101
	v_add_f32_e32 v98, v98, v102
	v_add_f32_e32 v98, v98, v103
	v_cndmask_b32_e32 v106, v170, v106, vcc
	v_add_f32_e32 v98, v98, v104
	v_lshlrev_b32_e32 v106, 2, v106
	v_add_f32_e32 v98, v98, v105
	ds_bpermute_b32 v99, v106, v98
	v_xor_b32_e32 v100, 32, v170
	v_cmp_lt_i32_e32 vcc, v100, v171
	s_waitcnt lgkmcnt(0)
	v_add_f32_e32 v98, v98, v99
	v_cndmask_b32_e32 v100, v170, v100, vcc
	v_lshlrev_b32_e32 v100, 2, v100
	ds_bpermute_b32 v99, v100, v98
	s_waitcnt lgkmcnt(0)
	v_add_f32_e32 v98, v98, v99
	v_fmamk_f32 v98, v98, 0x3a000000, v167
	v_mul_f32_e32 v99, 0x4b800000, v98
	v_cmp_gt_f32_e32 vcc, s33, v98
	s_nop 1
	v_cndmask_b32_e32 v98, v98, v99, vcc
	v_rsq_f32_e32 v98, v98
	s_nop 0
	v_mul_f32_e32 v99, 0x45800000, v98
	v_cndmask_b32_e32 v98, v98, v99, vcc

; __device__ __forceinline__ unsigned pk2(float lo, float hi) { return pg8::cvt_pk_bf16(lo, hi); }
; __device__ __forceinline__ float sigmoidf_(float x) { return __builtin_amdgcn_rcpf(1.f + fexp(-x)); }
;     __device__ __forceinline__ float rs(int r, int fq) const { return (r >> 8) == tab_pm ? tab[r & 255] : row_rstd(rowsq, r, fq); }
;     __device__ __forceinline__ float rs(int r, int fq) const { return (r >> 8) == tab_pm ? tab[r & 255] : row_rstd(rowsq, r, fq); }
; __device__ __forceinline__ float row_rstd(const float* part, int r, int fq) {
;     float s = 0.f;
; #pragma unroll
;     for (int k = 0; k < 8; ++k) s += part[(size_t)(fq * 8 + k) * MTOK + r];
;     s += __shfl_xor(s, 16); s += __shfl_xor(s, 32);
;     return rsqrtf(s * (1.f / DM) + EPS);
; }
;     __device__ __forceinline__ void operator()(const f32x4 (&acc)[2][2][4][2], const pg8::Unit& u, int wr, int wc, int fr, int fq) const {
;         const int row0 = u.pm * 256 + wr * 64 + fr;
; #pragma unroll
;         for (int ai = 0; ai < 2; ++ai)
; #pragma unroll
;             for (int m = 0; m < 4; ++m) {
;                 const int r = row0 + ai * 128 + m * 16;
;                 const float rstd = rs(r, fq);
;                 float o[2][4];
; #pragma unroll
;                 for (int bj = 0; bj < 2; ++bj) {
;                     const f32x4 gv = acc[ai][bj][m][0] * rstd, uv = acc[ai][bj][m][1] * rstd;
; #pragma unroll
;                     for (int i = 0; i < 4; ++i) o[bj][i] = gv[i] * sigmoidf_(gv[i]) * uv[i];
;                 }
;                 const int j0 = u.pn * 128 + wc * 32 + 8 * fq;
;                 u32x4 w; w.x = pk2(o[0][0], o[0][1]); w.y = pk2(o[0][2], o[0][3]); w.z = pk2(o[1][0], o[1][1]); w.w = pk2(o[1][2], o[1][3]);
;                 *(u32x4*)(HID + (size_t)r * DFF + j0) = w;
;             }
;     }
.LBB0_1426:
	s_waitcnt lgkmcnt(0)
	v_pk_mul_f32 v[92:93], v[92:93], v[98:99] op_sel_hi:[1,0]
	s_and_b64 vcc, exec, s[4:5]
	v_mul_f32_e32 v99, 0xbfb8aa3b, v92
	v_exp_f32_e32 v99, v99
	v_mul_f32_e32 v100, 0xbfb8aa3b, v93
	v_exp_f32_e32 v100, v100
	v_add_f32_e32 v99, 1.0, v99
	v_pk_mul_f32 v[94:95], v[94:95], v[98:99] op_sel_hi:[1,0]
	v_add_f32_e32 v101, 1.0, v100
	v_rcp_f32_e32 v100, v99
	v_mul_f32_e32 v99, 0xbfb8aa3b, v94
	v_exp_f32_e32 v99, v99
	v_mul_f32_e32 v102, 0xbfb8aa3b, v95
	v_exp_f32_e32 v103, v102
	v_rcp_f32_e32 v101, v101
	v_add_f32_e32 v99, 1.0, v99
	v_rcp_f32_e32 v102, v99
	v_add_f32_e32 v99, 1.0, v103
	v_rcp_f32_e32 v103, v99
	v_pk_mul_f32 v[92:93], v[92:93], v[100:101]
	v_pk_mul_f32 v[88:89], v[88:89], v[98:99] op_sel_hi:[1,0]
	v_pk_mul_f32 v[84:85], v[84:85], v[98:99] op_sel_hi:[1,0]
	v_pk_mul_f32 v[88:89], v[88:89], v[92:93]
	v_pk_mul_f32 v[92:93], v[94:95], v[102:103]
	v_mul_f32_e32 v94, 0xbfb8aa3b, v84
	v_mul_f32_e32 v95, 0xbfb8aa3b, v85
	v_exp_f32_e32 v94, v94
	v_exp_f32_e32 v95, v95
	v_pk_mul_f32 v[90:91], v[90:91], v[98:99] op_sel_hi:[1,0]
	v_pk_mul_f32 v[86:87], v[86:87], v[98:99] op_sel_hi:[1,0]
	v_pk_mul_f32 v[90:91], v[90:91], v[92:93]
	v_add_f32_e32 v92, 1.0, v94
	v_add_f32_e32 v93, 1.0, v95
	v_mul_f32_e32 v94, 0xbfb8aa3b, v86
	v_mul_f32_e32 v95, 0xbfb8aa3b, v87
	v_exp_f32_e32 v94, v94
	v_exp_f32_e32 v95, v95
	v_rcp_f32_e32 v92, v92
	v_rcp_f32_e32 v93, v93
	v_add_f32_e32 v94, 1.0, v94
	v_add_f32_e32 v95, 1.0, v95
	v_rcp_f32_e32 v94, v94
	v_rcp_f32_e32 v95, v95
	v_pk_mul_f32 v[84:85], v[84:85], v[92:93]
	v_pk_mul_f32 v[80:81], v[80:81], v[98:99] op_sel_hi:[1,0]
	v_pk_mul_f32 v[82:83], v[82:83], v[98:99] op_sel_hi:[1,0]
	v_pk_mul_f32 v[84:85], v[80:81], v[84:85]
	v_pk_mul_f32 v[80:81], v[86:87], v[94:95]
	s_nop 0
	v_pk_mul_f32 v[86:87], v[82:83], v[80:81]
	v_cvt_pk_bf16_f32 v82, v84, v85
	v_mov_b64_e32 v[84:85], s[8:9]
	v_mad_u64_u32 v[84:85], s[0:1], v96, s90, v[84:85]
	v_cvt_pk_bf16_f32 v83, v86, v87
	v_mov_b32_e32 v86, v85
	v_mad_u64_u32 v[86:87], s[0:1], v97, s90, v[86:87]
	v_mov_b32_e32 v85, v86
	v_cvt_pk_bf16_f32 v80, v88, v89
	v_cvt_pk_bf16_f32 v81, v90, v91
	v_lshl_add_u64 v[84:85], v[136:137], 1, v[84:85]
	global_store_dwordx4 v[84:85], v[80:83], off sc1
	s_mov_b64 s[0:1], -1
	s_nop 0
	v_or_b32_e32 v80, 48, v138
	v_ashrrev_i32_e32 v81, 31, v80
	s_cbranch_vccnz .LBB0_1428
	v_lshl_add_u64 v[82:83], v[138:139], 2, v[130:131]
	v_add_co_u32_e32 v84, vcc, 0x10000, v82
	s_mov_b64 s[0:1], 0
	s_nop 0
	v_addc_co_u32_e32 v85, vcc, 0, v83, vcc
	v_add_co_u32_e32 v86, vcc, 0x20000, v82
	s_nop 1
	v_addc_co_u32_e32 v87, vcc, 0, v83, vcc
	v_add_co_u32_e32 v88, vcc, 0x30000, v82
	s_nop 1
	v_addc_co_u32_e32 v89, vcc, 0, v83, vcc
	v_add_co_u32_e32 v90, vcc, 0x40000, v82
	s_nop 1
	v_addc_co_u32_e32 v91, vcc, 0, v83, vcc
	v_add_co_u32_e32 v92, vcc, 0x50000, v82
	s_nop 1
	v_addc_co_u32_e32 v93, vcc, 0, v83, vcc
	v_add_co_u32_e32 v94, vcc, 0x60000, v82
	s_nop 1
	v_addc_co_u32_e32 v95, vcc, 0, v83, vcc
	v_add_co_u32_e32 v96, vcc, 0x70000, v82
	s_nop 1
	v_addc_co_u32_e32 v97, vcc, 0, v83, vcc
	v_xor_b32_e32 v90, 16, v170
	v_cmp_lt_i32_e32 vcc, v90, v171
	s_waitcnt vmcnt(27)
	v_mov_b32_e32 v82, v252
	v_mov_b32_e32 v83, v253
	v_mov_b32_e32 v84, v188
	v_mov_b32_e32 v85, v189
	v_mov_b32_e32 v86, v190
	v_mov_b32_e32 v87, v191
	v_mov_b32_e32 v88, v192
	v_mov_b32_e32 v89, v193
	global_load_dword v252, v[194:195], off offset:704
	global_load_dword v253, v[196:197], off offset:704
	global_load_dword v188, v[198:199], off offset:704
	global_load_dword v189, v[200:201], off offset:704
	global_load_dword v190, v[202:203], off offset:704
	global_load_dword v191, v[204:205], off offset:704
	global_load_dword v192, v[206:207], off offset:704
	global_load_dword v193, v[208:209], off offset:704
	v_add_f32_e32 v82, 0, v82
	v_add_f32_e32 v82, v82, v83
	v_add_f32_e32 v82, v82, v84
	v_add_f32_e32 v82, v82, v85
	v_add_f32_e32 v82, v82, v86
	v_add_f32_e32 v82, v82, v87
	v_cndmask_b32_e32 v90, v170, v90, vcc
	v_add_f32_e32 v82, v82, v88
	v_lshlrev_b32_e32 v90, 2, v90
	v_add_f32_e32 v82, v82, v89
	ds_bpermute_b32 v83, v90, v82
	v_xor_b32_e32 v84, 32, v170
	v_cmp_lt_i32_e32 vcc, v84, v171
	s_waitcnt lgkmcnt(0)
	v_add_f32_e32 v82, v82, v83
	v_cndmask_b32_e32 v84, v170, v84, vcc
	v_lshlrev_b32_e32 v84, 2, v84
	ds_bpermute_b32 v83, v84, v82
	s_waitcnt lgkmcnt(0)
	v_add_f32_e32 v82, v82, v83
	v_fmamk_f32 v82, v82, 0x3a000000, v167
	v_mul_f32_e32 v83, 0x4b800000, v82
	v_cmp_gt_f32_e32 vcc, s33, v82
	s_nop 1
	v_cndmask_b32_e32 v82, v82, v83, vcc
	v_rsq_f32_e32 v82, v82
	s_nop 0
	v_mul_f32_e32 v83, 0x45800000, v82
	v_cndmask_b32_e32 v82, v82, v83, vcc

; __device__ __forceinline__ unsigned pk2(float lo, float hi) { return pg8::cvt_pk_bf16(lo, hi); }
; __device__ __forceinline__ float sigmoidf_(float x) { return __builtin_amdgcn_rcpf(1.f + fexp(-x)); }
;     __device__ __forceinline__ float rs(int r, int fq) const { return (r >> 8) == tab_pm ? tab[r & 255] : row_rstd(rowsq, r, fq); }
;     __device__ __forceinline__ float rs(int r, int fq) const { return (r >> 8) == tab_pm ? tab[r & 255] : row_rstd(rowsq, r, fq); }
; __device__ __forceinline__ float row_rstd(const float* part, int r, int fq) {
;     float s = 0.f;
; #pragma unroll
;     for (int k = 0; k < 8; ++k) s += part[(size_t)(fq * 8 + k) * MTOK + r];
;     s += __shfl_xor(s, 16); s += __shfl_xor(s, 32);
;     return rsqrtf(s * (1.f / DM) + EPS);
; }
;     __device__ __forceinline__ void operator()(const f32x4 (&acc)[2][2][4][2], const pg8::Unit& u, int wr, int wc, int fr, int fq) const {
;         const int row0 = u.pm * 256 + wr * 64 + fr;
; #pragma unroll
;         for (int ai = 0; ai < 2; ++ai)
; #pragma unroll
;             for (int m = 0; m < 4; ++m) {
;                 const int r = row0 + ai * 128 + m * 16;
;                 const float rstd = rs(r, fq);
;                 float o[2][4];
; #pragma unroll
;                 for (int bj = 0; bj < 2; ++bj) {
;                     const f32x4 gv = acc[ai][bj][m][0] * rstd, uv = acc[ai][bj][m][1] * rstd;
; #pragma unroll
;                     for (int i = 0; i < 4; ++i) o[bj][i] = gv[i] * sigmoidf_(gv[i]) * uv[i];
;                 }
;                 const int j0 = u.pn * 128 + wc * 32 + 8 * fq;
;                 u32x4 w; w.x = pk2(o[0][0], o[0][1]); w.y = pk2(o[0][2], o[0][3]); w.z = pk2(o[1][0], o[1][1]); w.w = pk2(o[1][2], o[1][3]);
;                 *(u32x4*)(HID + (size_t)r * DFF + j0) = w;
;             }
;     }
.LBB0_1430:
	s_waitcnt lgkmcnt(0)
	v_pk_mul_f32 v[76:77], v[76:77], v[82:83] op_sel_hi:[1,0]
	s_nop 0
	v_mul_f32_e32 v83, 0xbfb8aa3b, v76
	v_exp_f32_e32 v83, v83
	v_mul_f32_e32 v84, 0xbfb8aa3b, v77
	v_exp_f32_e32 v84, v84
	v_add_f32_e32 v83, 1.0, v83
	v_pk_mul_f32 v[78:79], v[78:79], v[82:83] op_sel_hi:[1,0]
	v_add_f32_e32 v85, 1.0, v84
	v_rcp_f32_e32 v84, v83
	v_mul_f32_e32 v83, 0xbfb8aa3b, v78
	v_exp_f32_e32 v83, v83
	v_mul_f32_e32 v86, 0xbfb8aa3b, v79
	v_exp_f32_e32 v87, v86
	v_rcp_f32_e32 v85, v85
	v_add_f32_e32 v83, 1.0, v83
	v_rcp_f32_e32 v86, v83
	v_add_f32_e32 v83, 1.0, v87
	v_rcp_f32_e32 v87, v83
	v_pk_mul_f32 v[76:77], v[76:77], v[84:85]
	v_pk_mul_f32 v[72:73], v[72:73], v[82:83] op_sel_hi:[1,0]
	v_pk_mul_f32 v[68:69], v[68:69], v[82:83] op_sel_hi:[1,0]
	v_pk_mul_f32 v[72:73], v[72:73], v[76:77]
	v_pk_mul_f32 v[76:77], v[78:79], v[86:87]
	v_mul_f32_e32 v78, 0xbfb8aa3b, v68
	v_mul_f32_e32 v79, 0xbfb8aa3b, v69
	v_exp_f32_e32 v78, v78
	v_exp_f32_e32 v79, v79
	v_pk_mul_f32 v[74:75], v[74:75], v[82:83] op_sel_hi:[1,0]
	v_pk_mul_f32 v[70:71], v[70:71], v[82:83] op_sel_hi:[1,0]
	v_pk_mul_f32 v[74:75], v[74:75], v[76:77]
	v_add_f32_e32 v76, 1.0, v78
	v_add_f32_e32 v77, 1.0, v79
	v_mul_f32_e32 v78, 0xbfb8aa3b, v70
	v_mul_f32_e32 v79, 0xbfb8aa3b, v71
	v_exp_f32_e32 v78, v78
	v_exp_f32_e32 v79, v79
	v_rcp_f32_e32 v76, v76
	v_rcp_f32_e32 v77, v77
	v_add_f32_e32 v78, 1.0, v78
	v_add_f32_e32 v79, 1.0, v79
	v_rcp_f32_e32 v78, v78
	v_rcp_f32_e32 v79, v79
	v_pk_mul_f32 v[68:69], v[68:69], v[76:77]
	v_pk_mul_f32 v[64:65], v[64:65], v[82:83] op_sel_hi:[1,0]
	v_pk_mul_f32 v[66:67], v[66:67], v[82:83] op_sel_hi:[1,0]
	v_pk_mul_f32 v[68:69], v[64:65], v[68:69]
	v_pk_mul_f32 v[64:65], v[70:71], v[78:79]
	s_nop 0
	v_pk_mul_f32 v[70:71], v[66:67], v[64:65]
	v_cvt_pk_bf16_f32 v66, v68, v69
	v_mov_b64_e32 v[68:69], s[8:9]
	v_mad_u64_u32 v[68:69], s[0:1], v80, s90, v[68:69]
	v_cvt_pk_bf16_f32 v67, v70, v71
	v_mov_b32_e32 v70, v69
	v_mad_u64_u32 v[70:71], s[0:1], v81, s90, v[70:71]
	v_mov_b32_e32 v69, v70
	v_cvt_pk_bf16_f32 v64, v72, v73
	v_cvt_pk_bf16_f32 v65, v74, v75
	v_lshl_add_u64 v[68:69], v[136:137], 1, v[68:69]
	global_store_dwordx4 v[68:69], v[64:67], off sc1
	s_nop 1
	v_add_u32_e32 v64, 0x80, v138
	v_ashrrev_i32_e32 v65, 8, v64
	v_cmp_ne_u32_e64 s[4:5], s29, v65
	v_ashrrev_i32_e32 v65, 31, v64
	s_and_saveexec_b64 s[0:1], s[4:5]
	s_xor_b64 s[0:1], exec, s[0:1]
	s_cbranch_execz .LBB0_1432
	v_lshl_add_u64 v[66:67], v[138:139], 2, v[130:131]
	v_add_co_u32_e32 v68, vcc, 0x10000, v66
	s_nop 1
	v_addc_co_u32_e32 v69, vcc, 0, v67, vcc
	v_add_co_u32_e32 v70, vcc, 0x20000, v66
	s_nop 1
	v_addc_co_u32_e32 v71, vcc, 0, v67, vcc
	v_add_co_u32_e32 v72, vcc, 0x30000, v66
	s_nop 1
	v_addc_co_u32_e32 v73, vcc, 0, v67, vcc
	v_add_co_u32_e32 v74, vcc, 0x40000, v66
	s_nop 1
	v_addc_co_u32_e32 v75, vcc, 0, v67, vcc
	v_add_co_u32_e32 v76, vcc, 0x50000, v66
	s_nop 1
	v_addc_co_u32_e32 v77, vcc, 0, v67, vcc
	v_add_co_u32_e32 v78, vcc, 0x60000, v66
	s_nop 1
	v_addc_co_u32_e32 v79, vcc, 0, v67, vcc
	v_add_co_u32_e32 v80, vcc, 0x70000, v66
	s_nop 1
	v_addc_co_u32_e32 v81, vcc, 0, v67, vcc
	v_xor_b32_e32 v74, 16, v170
	v_cmp_lt_i32_e32 vcc, v74, v171
	s_waitcnt vmcnt(28)
	v_mov_b32_e32 v66, v228
	v_mov_b32_e32 v67, v229
	v_mov_b32_e32 v68, v230
	v_mov_b32_e32 v69, v231
	v_mov_b32_e32 v70, v232
	v_mov_b32_e32 v71, v233
	v_mov_b32_e32 v72, v234
	v_mov_b32_e32 v73, v235
	v_add_f32_e32 v66, 0, v66
	v_add_f32_e32 v66, v66, v67
	v_add_f32_e32 v66, v66, v68
	v_add_f32_e32 v66, v66, v69
	v_add_f32_e32 v66, v66, v70
	v_add_f32_e32 v66, v66, v71
	v_cndmask_b32_e32 v74, v170, v74, vcc
	v_add_f32_e32 v66, v66, v72
	v_lshlrev_b32_e32 v74, 2, v74
	v_add_f32_e32 v66, v66, v73
	ds_bpermute_b32 v67, v74, v66
	v_xor_b32_e32 v68, 32, v170
	v_cmp_lt_i32_e32 vcc, v68, v171
	s_waitcnt lgkmcnt(0)
	v_add_f32_e32 v66, v66, v67
	v_cndmask_b32_e32 v68, v170, v68, vcc
	v_lshlrev_b32_e32 v68, 2, v68
	ds_bpermute_b32 v67, v68, v66
	s_waitcnt lgkmcnt(0)
	v_add_f32_e32 v66, v66, v67
	v_fmamk_f32 v66, v66, 0x3a000000, v167
	v_mul_f32_e32 v67, 0x4b800000, v66
	v_cmp_gt_f32_e32 vcc, s33, v66
	s_nop 1
	v_cndmask_b32_e32 v66, v66, v67, vcc
	v_rsq_f32_e32 v66, v66
	s_nop 0
	v_mul_f32_e32 v67, 0x45800000, v66
	v_cndmask_b32_e32 v66, v66, v67, vcc
; __device__ __forceinline__ unsigned pk2(float lo, float hi) { return pg8::cvt_pk_bf16(lo, hi); }
; __device__ __forceinline__ float sigmoidf_(float x) { return __builtin_amdgcn_rcpf(1.f + fexp(-x)); }
;     __device__ __forceinline__ float rs(int r, int fq) const { return (r >> 8) == tab_pm ? tab[r & 255] : row_rstd(rowsq, r, fq); }
; __device__ __forceinline__ float row_rstd(const float* part, int r, int fq) {
;     float s = 0.f;
; #pragma unroll
;     for (int k = 0; k < 8; ++k) s += part[(size_t)(fq * 8 + k) * MTOK + r];
;     s += __shfl_xor(s, 16); s += __shfl_xor(s, 32);
;     return rsqrtf(s * (1.f / DM) + EPS);
; }
;     __device__ __forceinline__ float rs(int r, int fq) const { return (r >> 8) == tab_pm ? tab[r & 255] : row_rstd(rowsq, r, fq); }
;     __device__ __forceinline__ void operator()(const f32x4 (&acc)[2][2][4][2], const pg8::Unit& u, int wr, int wc, int fr, int fq) const {
;         const int row0 = u.pm * 256 + wr * 64 + fr;
; #pragma unroll
;         for (int ai = 0; ai < 2; ++ai)
; #pragma unroll
;             for (int m = 0; m < 4; ++m) {
;                 const int r = row0 + ai * 128 + m * 16;
;                 const float rstd = rs(r, fq);
;                 float o[2][4];
; #pragma unroll
;                 for (int bj = 0; bj < 2; ++bj) {
;                     const f32x4 gv = acc[ai][bj][m][0] * rstd, uv = acc[ai][bj][m][1] * rstd;
; #pragma unroll
;                     for (int i = 0; i < 4; ++i) o[bj][i] = gv[i] * sigmoidf_(gv[i]) * uv[i];
;                 }
;                 const int j0 = u.pn * 128 + wc * 32 + 8 * fq;
;                 u32x4 w; w.x = pk2(o[0][0], o[0][1]); w.y = pk2(o[0][2], o[0][3]); w.z = pk2(o[1][0], o[1][1]); w.w = pk2(o[1][2], o[1][3]);
;                 *(u32x4*)(HID + (size_t)r * DFF + j0) = w;
;             }
;     }
.LBB0_1432:
	s_andn2_saveexec_b64 s[0:1], s[0:1]
	v_and_b32_e32 v66, 0xcf, v64
	v_lshl_add_u32 v66, v66, 2, 0
	v_add_u32_e32 v66, 0x20000, v66
	ds_read_b32 v66, v66
	s_or_b64 exec, exec, s[0:1]
	s_waitcnt lgkmcnt(0)
	v_pk_mul_f32 v[60:61], v[60:61], v[66:67] op_sel_hi:[1,0]
	s_nop 0
	v_mul_f32_e32 v67, 0xbfb8aa3b, v60
	v_exp_f32_e32 v67, v67
	v_mul_f32_e32 v68, 0xbfb8aa3b, v61
	v_exp_f32_e32 v68, v68
	v_add_f32_e32 v67, 1.0, v67
	v_pk_mul_f32 v[62:63], v[62:63], v[66:67] op_sel_hi:[1,0]
	v_add_f32_e32 v69, 1.0, v68
	v_rcp_f32_e32 v68, v67
	v_mul_f32_e32 v67, 0xbfb8aa3b, v62
	v_exp_f32_e32 v67, v67
	v_mul_f32_e32 v70, 0xbfb8aa3b, v63
	v_exp_f32_e32 v71, v70
	v_rcp_f32_e32 v69, v69
	v_add_f32_e32 v67, 1.0, v67
	v_rcp_f32_e32 v70, v67
	v_add_f32_e32 v67, 1.0, v71
	v_rcp_f32_e32 v71, v67
	v_pk_mul_f32 v[60:61], v[60:61], v[68:69]
	v_pk_mul_f32 v[56:57], v[56:57], v[66:67] op_sel_hi:[1,0]
	v_pk_mul_f32 v[52:53], v[52:53], v[66:67] op_sel_hi:[1,0]
	v_pk_mul_f32 v[56:57], v[56:57], v[60:61]
	v_pk_mul_f32 v[60:61], v[62:63], v[70:71]
	v_mul_f32_e32 v62, 0xbfb8aa3b, v52
	v_mul_f32_e32 v63, 0xbfb8aa3b, v53
	v_exp_f32_e32 v62, v62
	v_exp_f32_e32 v63, v63
	v_pk_mul_f32 v[58:59], v[58:59], v[66:67] op_sel_hi:[1,0]
	v_pk_mul_f32 v[54:55], v[54:55], v[66:67] op_sel_hi:[1,0]
	v_pk_mul_f32 v[58:59], v[58:59], v[60:61]
	v_add_f32_e32 v60, 1.0, v62
	v_add_f32_e32 v61, 1.0, v63
	v_mul_f32_e32 v62, 0xbfb8aa3b, v54
	v_mul_f32_e32 v63, 0xbfb8aa3b, v55
	v_exp_f32_e32 v62, v62
	v_exp_f32_e32 v63, v63
	v_rcp_f32_e32 v60, v60
	v_rcp_f32_e32 v61, v61
	v_add_f32_e32 v62, 1.0, v62
	v_add_f32_e32 v63, 1.0, v63
	v_rcp_f32_e32 v62, v62
	v_rcp_f32_e32 v63, v63
	v_pk_mul_f32 v[52:53], v[52:53], v[60:61]
	v_pk_mul_f32 v[48:49], v[48:49], v[66:67] op_sel_hi:[1,0]
	v_pk_mul_f32 v[50:51], v[50:51], v[66:67] op_sel_hi:[1,0]
	v_pk_mul_f32 v[52:53], v[48:49], v[52:53]
	v_pk_mul_f32 v[48:49], v[54:55], v[62:63]
	s_nop 0
	v_pk_mul_f32 v[54:55], v[50:51], v[48:49]
	v_cvt_pk_bf16_f32 v50, v52, v53
	v_mov_b64_e32 v[52:53], s[8:9]
	v_mad_u64_u32 v[52:53], s[0:1], v64, s90, v[52:53]
	v_cvt_pk_bf16_f32 v51, v54, v55
	v_mov_b32_e32 v54, v53
	v_mad_u64_u32 v[54:55], s[0:1], v65, s90, v[54:55]
	v_mov_b32_e32 v53, v54
	v_cvt_pk_bf16_f32 v48, v56, v57
	v_cvt_pk_bf16_f32 v49, v58, v59
	v_lshl_add_u64 v[52:53], v[136:137], 1, v[52:53]
	global_store_dwordx4 v[52:53], v[48:51], off sc1
	s_nop 1
	v_add_u32_e32 v48, 0x90, v138
	v_ashrrev_i32_e32 v49, 31, v48
	s_and_saveexec_b64 s[0:1], s[4:5]
	s_xor_b64 s[0:1], exec, s[0:1]
	s_cbranch_execz .LBB0_1436
	v_lshl_add_u64 v[50:51], v[138:139], 2, v[130:131]
	v_add_co_u32_e32 v52, vcc, 0x10000, v50
	s_nop 1
	v_addc_co_u32_e32 v53, vcc, 0, v51, vcc
	v_add_co_u32_e32 v54, vcc, 0x20000, v50
	s_nop 1
	v_addc_co_u32_e32 v55, vcc, 0, v51, vcc
	v_add_co_u32_e32 v56, vcc, 0x30000, v50
	s_nop 1
	v_addc_co_u32_e32 v57, vcc, 0, v51, vcc
	v_add_co_u32_e32 v58, vcc, 0x40000, v50
	s_nop 1
	v_addc_co_u32_e32 v59, vcc, 0, v51, vcc
	v_add_co_u32_e32 v60, vcc, 0x50000, v50
	s_nop 1
	v_addc_co_u32_e32 v61, vcc, 0, v51, vcc
	v_add_co_u32_e32 v62, vcc, 0x60000, v50
	s_nop 1
	v_addc_co_u32_e32 v63, vcc, 0, v51, vcc
	v_add_co_u32_e32 v64, vcc, 0x70000, v50
	s_nop 1
	v_addc_co_u32_e32 v65, vcc, 0, v51, vcc
	v_xor_b32_e32 v58, 16, v170
	v_cmp_lt_i32_e32 vcc, v58, v171
	s_waitcnt vmcnt(21)
	v_mov_b32_e32 v50, v236
	v_mov_b32_e32 v51, v237
	v_mov_b32_e32 v52, v238
	v_mov_b32_e32 v53, v239
	v_mov_b32_e32 v54, v240
	v_mov_b32_e32 v55, v241
	v_mov_b32_e32 v56, v242
	v_mov_b32_e32 v57, v243
	v_add_f32_e32 v50, 0, v50
	v_add_f32_e32 v50, v50, v51
	v_add_f32_e32 v50, v50, v52
	v_add_f32_e32 v50, v50, v53
	v_add_f32_e32 v50, v50, v54
	v_add_f32_e32 v50, v50, v55
	v_cndmask_b32_e32 v58, v170, v58, vcc
	v_add_f32_e32 v50, v50, v56
	v_lshlrev_b32_e32 v58, 2, v58
	v_add_f32_e32 v50, v50, v57
	ds_bpermute_b32 v51, v58, v50
	v_xor_b32_e32 v52, 32, v170
	v_cmp_lt_i32_e32 vcc, v52, v171
	s_waitcnt lgkmcnt(0)
	v_add_f32_e32 v50, v50, v51
	v_cndmask_b32_e32 v52, v170, v52, vcc
	v_lshlrev_b32_e32 v52, 2, v52
	ds_bpermute_b32 v51, v52, v50
	s_waitcnt lgkmcnt(0)
	v_add_f32_e32 v50, v50, v51
	v_fmamk_f32 v50, v50, 0x3a000000, v167
	v_mul_f32_e32 v51, 0x4b800000, v50
	v_cmp_gt_f32_e32 vcc, s33, v50
	s_nop 1
	v_cndmask_b32_e32 v50, v50, v51, vcc
	v_rsq_f32_e32 v50, v50
	s_nop 0
	v_mul_f32_e32 v51, 0x45800000, v50
	v_cndmask_b32_e32 v50, v50, v51, vcc
; __device__ __forceinline__ unsigned pk2(float lo, float hi) { return pg8::cvt_pk_bf16(lo, hi); }
; __device__ __forceinline__ float sigmoidf_(float x) { return __builtin_amdgcn_rcpf(1.f + fexp(-x)); }
;     __device__ __forceinline__ float rs(int r, int fq) const { return (r >> 8) == tab_pm ? tab[r & 255] : row_rstd(rowsq, r, fq); }
; __device__ __forceinline__ float row_rstd(const float* part, int r, int fq) {
;     float s = 0.f;
; #pragma unroll
;     for (int k = 0; k < 8; ++k) s += part[(size_t)(fq * 8 + k) * MTOK + r];
;     s += __shfl_xor(s, 16); s += __shfl_xor(s, 32);
;     return rsqrtf(s * (1.f / DM) + EPS);
; }
;     __device__ __forceinline__ float rs(int r, int fq) const { return (r >> 8) == tab_pm ? tab[r & 255] : row_rstd(rowsq, r, fq); }
;     __device__ __forceinline__ void operator()(const f32x4 (&acc)[2][2][4][2], const pg8::Unit& u, int wr, int wc, int fr, int fq) const {
;         const int row0 = u.pm * 256 + wr * 64 + fr;
; #pragma unroll
;         for (int ai = 0; ai < 2; ++ai)
; #pragma unroll
;             for (int m = 0; m < 4; ++m) {
;                 const int r = row0 + ai * 128 + m * 16;
;                 const float rstd = rs(r, fq);
;                 float o[2][4];
; #pragma unroll
;                 for (int bj = 0; bj < 2; ++bj) {
;                     const f32x4 gv = acc[ai][bj][m][0] * rstd, uv = acc[ai][bj][m][1] * rstd;
; #pragma unroll
;                     for (int i = 0; i < 4; ++i) o[bj][i] = gv[i] * sigmoidf_(gv[i]) * uv[i];
;                 }
;                 const int j0 = u.pn * 128 + wc * 32 + 8 * fq;
;                 u32x4 w; w.x = pk2(o[0][0], o[0][1]); w.y = pk2(o[0][2], o[0][3]); w.z = pk2(o[1][0], o[1][1]); w.w = pk2(o[1][2], o[1][3]);
;                 *(u32x4*)(HID + (size_t)r * DFF + j0) = w;
;             }
;     }
.LBB0_1436:
	s_andn2_saveexec_b64 s[0:1], s[0:1]
	v_and_b32_e32 v50, 0xdf, v48
	v_lshl_add_u32 v50, v50, 2, 0
	v_add_u32_e32 v50, 0x20000, v50
	ds_read_b32 v50, v50
	s_or_b64 exec, exec, s[0:1]
	s_waitcnt lgkmcnt(0)
	v_pk_mul_f32 v[44:45], v[44:45], v[50:51] op_sel_hi:[1,0]
	s_nop 0
	v_mul_f32_e32 v51, 0xbfb8aa3b, v44
	v_exp_f32_e32 v51, v51
	v_mul_f32_e32 v52, 0xbfb8aa3b, v45
	v_exp_f32_e32 v52, v52
	v_add_f32_e32 v51, 1.0, v51
	v_pk_mul_f32 v[46:47], v[46:47], v[50:51] op_sel_hi:[1,0]
	v_add_f32_e32 v53, 1.0, v52
	v_rcp_f32_e32 v52, v51
	v_mul_f32_e32 v51, 0xbfb8aa3b, v46
	v_exp_f32_e32 v51, v51
	v_mul_f32_e32 v54, 0xbfb8aa3b, v47
	v_exp_f32_e32 v55, v54
	v_rcp_f32_e32 v53, v53
	v_add_f32_e32 v51, 1.0, v51
	v_rcp_f32_e32 v54, v51
	v_add_f32_e32 v51, 1.0, v55
	v_rcp_f32_e32 v55, v51
	v_pk_mul_f32 v[44:45], v[44:45], v[52:53]
	v_pk_mul_f32 v[40:41], v[40:41], v[50:51] op_sel_hi:[1,0]
	v_pk_mul_f32 v[36:37], v[36:37], v[50:51] op_sel_hi:[1,0]
	v_pk_mul_f32 v[40:41], v[40:41], v[44:45]
	v_pk_mul_f32 v[44:45], v[46:47], v[54:55]
	v_mul_f32_e32 v46, 0xbfb8aa3b, v36
	v_mul_f32_e32 v47, 0xbfb8aa3b, v37
	v_exp_f32_e32 v46, v46
	v_exp_f32_e32 v47, v47
	v_pk_mul_f32 v[42:43], v[42:43], v[50:51] op_sel_hi:[1,0]
	v_pk_mul_f32 v[38:39], v[38:39], v[50:51] op_sel_hi:[1,0]
	v_pk_mul_f32 v[42:43], v[42:43], v[44:45]
	v_add_f32_e32 v44, 1.0, v46
	v_add_f32_e32 v45, 1.0, v47
	v_mul_f32_e32 v46, 0xbfb8aa3b, v38
	v_mul_f32_e32 v47, 0xbfb8aa3b, v39
	v_exp_f32_e32 v46, v46
	v_exp_f32_e32 v47, v47
	v_rcp_f32_e32 v44, v44
	v_rcp_f32_e32 v45, v45
	v_add_f32_e32 v46, 1.0, v46
	v_add_f32_e32 v47, 1.0, v47
	v_rcp_f32_e32 v46, v46
	v_rcp_f32_e32 v47, v47
	v_pk_mul_f32 v[36:37], v[36:37], v[44:45]
	v_pk_mul_f32 v[32:33], v[32:33], v[50:51] op_sel_hi:[1,0]
	v_pk_mul_f32 v[34:35], v[34:35], v[50:51] op_sel_hi:[1,0]
	v_pk_mul_f32 v[36:37], v[32:33], v[36:37]
	v_pk_mul_f32 v[32:33], v[38:39], v[46:47]
	s_nop 0
	v_pk_mul_f32 v[38:39], v[34:35], v[32:33]
	v_cvt_pk_bf16_f32 v34, v36, v37
	v_mov_b64_e32 v[36:37], s[8:9]
	v_mad_u64_u32 v[36:37], s[0:1], v48, s90, v[36:37]
	v_cvt_pk_bf16_f32 v35, v38, v39
	v_mov_b32_e32 v38, v37
	v_mad_u64_u32 v[38:39], s[0:1], v49, s90, v[38:39]
	v_mov_b32_e32 v37, v38
	v_cvt_pk_bf16_f32 v32, v40, v41
	v_cvt_pk_bf16_f32 v33, v42, v43
	v_lshl_add_u64 v[36:37], v[136:137], 1, v[36:37]
	global_store_dwordx4 v[36:37], v[32:35], off sc1
	s_nop 1
	v_add_u32_e32 v32, 0xa0, v138
	v_ashrrev_i32_e32 v33, 31, v32
	s_and_saveexec_b64 s[0:1], s[4:5]
	s_xor_b64 s[0:1], exec, s[0:1]
	s_cbranch_execz .LBB0_1440
	v_lshl_add_u64 v[34:35], v[138:139], 2, v[130:131]
	v_add_co_u32_e32 v36, vcc, 0x10000, v34
	s_nop 1
	v_addc_co_u32_e32 v37, vcc, 0, v35, vcc
	v_add_co_u32_e32 v38, vcc, 0x20000, v34
	s_nop 1
	v_addc_co_u32_e32 v39, vcc, 0, v35, vcc
	v_add_co_u32_e32 v40, vcc, 0x30000, v34
	s_nop 1
	v_addc_co_u32_e32 v41, vcc, 0, v35, vcc
	v_add_co_u32_e32 v42, vcc, 0x40000, v34
	s_nop 1
	v_addc_co_u32_e32 v43, vcc, 0, v35, vcc
	v_add_co_u32_e32 v44, vcc, 0x50000, v34
	s_nop 1
	v_addc_co_u32_e32 v45, vcc, 0, v35, vcc
	v_add_co_u32_e32 v46, vcc, 0x60000, v34
	s_nop 1
	v_addc_co_u32_e32 v47, vcc, 0, v35, vcc
	v_add_co_u32_e32 v48, vcc, 0x70000, v34
	s_nop 1
	v_addc_co_u32_e32 v49, vcc, 0, v35, vcc
	v_xor_b32_e32 v42, 16, v170
	v_cmp_lt_i32_e32 vcc, v42, v171
	s_waitcnt vmcnt(13)
	v_mov_b32_e32 v34, v244
	v_mov_b32_e32 v35, v245
	v_mov_b32_e32 v36, v246
	v_mov_b32_e32 v37, v247
	v_mov_b32_e32 v38, v248
	v_mov_b32_e32 v39, v249
	v_mov_b32_e32 v40, v250
	v_mov_b32_e32 v41, v251
	v_add_f32_e32 v34, 0, v34
	v_add_f32_e32 v34, v34, v35
	v_add_f32_e32 v34, v34, v36
	v_add_f32_e32 v34, v34, v37
	v_add_f32_e32 v34, v34, v38
	v_add_f32_e32 v34, v34, v39
	v_cndmask_b32_e32 v42, v170, v42, vcc
	v_add_f32_e32 v34, v34, v40
	v_lshlrev_b32_e32 v42, 2, v42
	v_add_f32_e32 v34, v34, v41
	ds_bpermute_b32 v35, v42, v34
	v_xor_b32_e32 v36, 32, v170
	v_cmp_lt_i32_e32 vcc, v36, v171
	s_waitcnt lgkmcnt(0)
	v_add_f32_e32 v34, v34, v35
	v_cndmask_b32_e32 v36, v170, v36, vcc
	v_lshlrev_b32_e32 v36, 2, v36
	ds_bpermute_b32 v35, v36, v34
	s_waitcnt lgkmcnt(0)
	v_add_f32_e32 v34, v34, v35
	v_fmamk_f32 v34, v34, 0x3a000000, v167
	v_mul_f32_e32 v35, 0x4b800000, v34
	v_cmp_gt_f32_e32 vcc, s33, v34
	s_nop 1
	v_cndmask_b32_e32 v34, v34, v35, vcc
	v_rsq_f32_e32 v34, v34
	s_nop 0
	v_mul_f32_e32 v35, 0x45800000, v34
	v_cndmask_b32_e32 v34, v34, v35, vcc
; __device__ __forceinline__ unsigned pk2(float lo, float hi) { return pg8::cvt_pk_bf16(lo, hi); }
; __device__ __forceinline__ float sigmoidf_(float x) { return __builtin_amdgcn_rcpf(1.f + fexp(-x)); }
;     __device__ __forceinline__ float rs(int r, int fq) const { return (r >> 8) == tab_pm ? tab[r & 255] : row_rstd(rowsq, r, fq); }
; __device__ __forceinline__ float row_rstd(const float* part, int r, int fq) {
;     float s = 0.f;
; #pragma unroll
;     for (int k = 0; k < 8; ++k) s += part[(size_t)(fq * 8 + k) * MTOK + r];
;     s += __shfl_xor(s, 16); s += __shfl_xor(s, 32);
;     return rsqrtf(s * (1.f / DM) + EPS);
; }
;     __device__ __forceinline__ float rs(int r, int fq) const { return (r >> 8) == tab_pm ? tab[r & 255] : row_rstd(rowsq, r, fq); }
;     __device__ __forceinline__ void operator()(const f32x4 (&acc)[2][2][4][2], const pg8::Unit& u, int wr, int wc, int fr, int fq) const {
;         const int row0 = u.pm * 256 + wr * 64 + fr;
; #pragma unroll
;         for (int ai = 0; ai < 2; ++ai)
; #pragma unroll
;             for (int m = 0; m < 4; ++m) {
;                 const int r = row0 + ai * 128 + m * 16;
;                 const float rstd = rs(r, fq);
;                 float o[2][4];
; #pragma unroll
;                 for (int bj = 0; bj < 2; ++bj) {
;                     const f32x4 gv = acc[ai][bj][m][0] * rstd, uv = acc[ai][bj][m][1] * rstd;
; #pragma unroll
;                     for (int i = 0; i < 4; ++i) o[bj][i] = gv[i] * sigmoidf_(gv[i]) * uv[i];
;                 }
;                 const int j0 = u.pn * 128 + wc * 32 + 8 * fq;
;                 u32x4 w; w.x = pk2(o[0][0], o[0][1]); w.y = pk2(o[0][2], o[0][3]); w.z = pk2(o[1][0], o[1][1]); w.w = pk2(o[1][2], o[1][3]);
;                 *(u32x4*)(HID + (size_t)r * DFF + j0) = w;
;             }
;     }
.LBB0_1440:
	s_andn2_saveexec_b64 s[0:1], s[0:1]
	v_and_b32_e32 v34, 0xef, v32
	v_lshl_add_u32 v34, v34, 2, 0
	v_add_u32_e32 v34, 0x20000, v34
	ds_read_b32 v34, v34
	s_or_b64 exec, exec, s[0:1]
	s_waitcnt lgkmcnt(0)
	v_pk_mul_f32 v[28:29], v[28:29], v[34:35] op_sel_hi:[1,0]
	s_nop 0
	v_mul_f32_e32 v35, 0xbfb8aa3b, v28
	v_exp_f32_e32 v35, v35
	v_mul_f32_e32 v36, 0xbfb8aa3b, v29
	v_exp_f32_e32 v36, v36
	v_add_f32_e32 v35, 1.0, v35
	v_pk_mul_f32 v[30:31], v[30:31], v[34:35] op_sel_hi:[1,0]
	v_add_f32_e32 v37, 1.0, v36
	v_rcp_f32_e32 v36, v35
	v_mul_f32_e32 v35, 0xbfb8aa3b, v30
	v_exp_f32_e32 v35, v35
	v_mul_f32_e32 v38, 0xbfb8aa3b, v31
	v_exp_f32_e32 v39, v38
	v_rcp_f32_e32 v37, v37
	v_add_f32_e32 v35, 1.0, v35
	v_rcp_f32_e32 v38, v35
	v_add_f32_e32 v35, 1.0, v39
	v_rcp_f32_e32 v39, v35
	v_pk_mul_f32 v[28:29], v[28:29], v[36:37]
	v_pk_mul_f32 v[24:25], v[24:25], v[34:35] op_sel_hi:[1,0]
	v_pk_mul_f32 v[20:21], v[20:21], v[34:35] op_sel_hi:[1,0]
	v_pk_mul_f32 v[24:25], v[24:25], v[28:29]
	v_pk_mul_f32 v[28:29], v[30:31], v[38:39]
	v_mul_f32_e32 v30, 0xbfb8aa3b, v20
	v_mul_f32_e32 v31, 0xbfb8aa3b, v21
	v_exp_f32_e32 v30, v30
	v_exp_f32_e32 v31, v31
	v_pk_mul_f32 v[26:27], v[26:27], v[34:35] op_sel_hi:[1,0]
	v_pk_mul_f32 v[22:23], v[22:23], v[34:35] op_sel_hi:[1,0]
	v_pk_mul_f32 v[26:27], v[26:27], v[28:29]
	v_add_f32_e32 v28, 1.0, v30
	v_add_f32_e32 v29, 1.0, v31
	v_mul_f32_e32 v30, 0xbfb8aa3b, v22
	v_mul_f32_e32 v31, 0xbfb8aa3b, v23
	v_exp_f32_e32 v30, v30
	v_exp_f32_e32 v31, v31
	v_rcp_f32_e32 v28, v28
	v_rcp_f32_e32 v29, v29
	v_add_f32_e32 v30, 1.0, v30
	v_add_f32_e32 v31, 1.0, v31
	v_rcp_f32_e32 v30, v30
	v_rcp_f32_e32 v31, v31
	v_pk_mul_f32 v[20:21], v[20:21], v[28:29]
	v_pk_mul_f32 v[16:17], v[16:17], v[34:35] op_sel_hi:[1,0]
	v_pk_mul_f32 v[18:19], v[18:19], v[34:35] op_sel_hi:[1,0]
	v_pk_mul_f32 v[20:21], v[16:17], v[20:21]
	v_pk_mul_f32 v[16:17], v[22:23], v[30:31]
	s_nop 0
	v_pk_mul_f32 v[22:23], v[18:19], v[16:17]
	v_cvt_pk_bf16_f32 v18, v20, v21
	v_mov_b64_e32 v[20:21], s[8:9]
	v_mad_u64_u32 v[20:21], s[0:1], v32, s90, v[20:21]
	v_cvt_pk_bf16_f32 v19, v22, v23
	v_mov_b32_e32 v22, v21
	v_mad_u64_u32 v[22:23], s[0:1], v33, s90, v[22:23]
	v_mov_b32_e32 v21, v22
	v_cvt_pk_bf16_f32 v16, v24, v25
	v_cvt_pk_bf16_f32 v17, v26, v27
	v_lshl_add_u64 v[20:21], v[136:137], 1, v[20:21]
	global_store_dwordx4 v[20:21], v[16:19], off sc1
	s_nop 1
	v_add_u32_e32 v16, 0xb0, v138
	v_ashrrev_i32_e32 v17, 31, v16
	s_and_saveexec_b64 s[0:1], s[4:5]
	s_xor_b64 s[0:1], exec, s[0:1]
	s_cbranch_execz .LBB0_1444
	v_lshl_add_u64 v[18:19], v[138:139], 2, v[130:131]
	v_add_co_u32_e32 v20, vcc, 0x10000, v18
	s_nop 1
	v_addc_co_u32_e32 v21, vcc, 0, v19, vcc
	v_add_co_u32_e32 v22, vcc, 0x20000, v18
	s_nop 1
	v_addc_co_u32_e32 v23, vcc, 0, v19, vcc
	v_add_co_u32_e32 v24, vcc, 0x30000, v18
	s_nop 1
	v_addc_co_u32_e32 v25, vcc, 0, v19, vcc
	v_add_co_u32_e32 v26, vcc, 0x40000, v18
	s_nop 1
	v_addc_co_u32_e32 v27, vcc, 0, v19, vcc
	v_add_co_u32_e32 v28, vcc, 0x50000, v18
	s_nop 1
	v_addc_co_u32_e32 v29, vcc, 0, v19, vcc
	v_add_co_u32_e32 v30, vcc, 0x60000, v18
	s_nop 1
	v_addc_co_u32_e32 v31, vcc, 0, v19, vcc
	v_add_co_u32_e32 v32, vcc, 0x70000, v18
	s_nop 1
	v_addc_co_u32_e32 v33, vcc, 0, v19, vcc
	v_xor_b32_e32 v26, 16, v170
	v_cmp_lt_i32_e32 vcc, v26, v171
	s_waitcnt vmcnt(4)
	v_mov_b32_e32 v18, v252
	v_mov_b32_e32 v19, v253
	v_mov_b32_e32 v20, v188
	v_mov_b32_e32 v21, v189
	v_mov_b32_e32 v22, v190
	v_mov_b32_e32 v23, v191
	v_mov_b32_e32 v24, v192
	v_mov_b32_e32 v25, v193
	v_add_f32_e32 v18, 0, v18
	v_add_f32_e32 v18, v18, v19
	v_add_f32_e32 v18, v18, v20
	v_add_f32_e32 v18, v18, v21
	v_add_f32_e32 v18, v18, v22
	v_add_f32_e32 v18, v18, v23
	v_cndmask_b32_e32 v26, v170, v26, vcc
	v_add_f32_e32 v18, v18, v24
	v_lshlrev_b32_e32 v26, 2, v26
	v_add_f32_e32 v18, v18, v25
	ds_bpermute_b32 v19, v26, v18
	v_xor_b32_e32 v20, 32, v170
	v_cmp_lt_i32_e32 vcc, v20, v171
	s_waitcnt lgkmcnt(0)
	v_add_f32_e32 v18, v18, v19
	v_cndmask_b32_e32 v20, v170, v20, vcc
	v_lshlrev_b32_e32 v20, 2, v20
	ds_bpermute_b32 v19, v20, v18
	s_waitcnt lgkmcnt(0)
	v_add_f32_e32 v18, v18, v19
	v_fmamk_f32 v18, v18, 0x3a000000, v167
	v_mul_f32_e32 v19, 0x4b800000, v18
	v_cmp_gt_f32_e32 vcc, s33, v18
	s_nop 1
	v_cndmask_b32_e32 v18, v18, v19, vcc
	v_rsq_f32_e32 v18, v18
	s_nop 0
	v_mul_f32_e32 v19, 0x45800000, v18
	v_cndmask_b32_e32 v18, v18, v19, vcc
.LBB0_1444:
	s_andn2_saveexec_b64 s[0:1], s[0:1]
	v_and_b32_e32 v18, 0xff, v16
	v_lshl_add_u32 v18, v18, 2, 0
	v_add_u32_e32 v18, 0x20000, v18
	ds_read_b32 v18, v18
	s_or_b64 exec, exec, s[0:1]
	s_waitcnt lgkmcnt(0)
	v_pk_mul_f32 v[12:13], v[12:13], v[18:19] op_sel_hi:[1,0]
	s_andn2_b64 vcc, exec, s[2:3]
	v_mul_f32_e32 v19, 0xbfb8aa3b, v12
	v_exp_f32_e32 v19, v19
	v_mul_f32_e32 v20, 0xbfb8aa3b, v13
	v_exp_f32_e32 v20, v20
	v_add_f32_e32 v19, 1.0, v19
	v_pk_mul_f32 v[14:15], v[14:15], v[18:19] op_sel_hi:[1,0]
	v_add_f32_e32 v21, 1.0, v20
	v_rcp_f32_e32 v20, v19
	v_mul_f32_e32 v19, 0xbfb8aa3b, v14
	v_exp_f32_e32 v19, v19
	v_mul_f32_e32 v22, 0xbfb8aa3b, v15
	v_exp_f32_e32 v23, v22
	v_rcp_f32_e32 v21, v21
	v_add_f32_e32 v19, 1.0, v19
	v_rcp_f32_e32 v22, v19
	v_add_f32_e32 v19, 1.0, v23
	v_rcp_f32_e32 v23, v19
	v_pk_mul_f32 v[12:13], v[12:13], v[20:21]
	v_pk_mul_f32 v[8:9], v[8:9], v[18:19] op_sel_hi:[1,0]
	v_pk_mul_f32 v[4:5], v[4:5], v[18:19] op_sel_hi:[1,0]
	v_pk_mul_f32 v[8:9], v[8:9], v[12:13]
	v_pk_mul_f32 v[12:13], v[14:15], v[22:23]
	v_mul_f32_e32 v14, 0xbfb8aa3b, v4
	v_mul_f32_e32 v15, 0xbfb8aa3b, v5
	v_exp_f32_e32 v14, v14
	v_exp_f32_e32 v15, v15
	v_pk_mul_f32 v[10:11], v[10:11], v[18:19] op_sel_hi:[1,0]
	v_pk_mul_f32 v[6:7], v[6:7], v[18:19] op_sel_hi:[1,0]
	v_pk_mul_f32 v[10:11], v[10:11], v[12:13]
	v_add_f32_e32 v12, 1.0, v14
	v_add_f32_e32 v13, 1.0, v15
	v_mul_f32_e32 v14, 0xbfb8aa3b, v6
	v_mul_f32_e32 v15, 0xbfb8aa3b, v7
	v_exp_f32_e32 v14, v14
	v_exp_f32_e32 v15, v15
	v_rcp_f32_e32 v12, v12
	v_rcp_f32_e32 v13, v13
	v_add_f32_e32 v14, 1.0, v14
	v_add_f32_e32 v15, 1.0, v15
	v_rcp_f32_e32 v14, v14
	v_rcp_f32_e32 v15, v15
	v_pk_mul_f32 v[4:5], v[4:5], v[12:13]
	v_pk_mul_f32 v[0:1], v[0:1], v[18:19] op_sel_hi:[1,0]
	v_pk_mul_f32 v[2:3], v[2:3], v[18:19] op_sel_hi:[1,0]
	v_pk_mul_f32 v[4:5], v[0:1], v[4:5]
	v_pk_mul_f32 v[0:1], v[6:7], v[14:15]
	s_nop 0
	v_pk_mul_f32 v[6:7], v[2:3], v[0:1]
	v_cvt_pk_bf16_f32 v2, v4, v5
	v_mov_b64_e32 v[4:5], s[8:9]
	v_mad_u64_u32 v[4:5], s[0:1], v16, s90, v[4:5]
	v_cvt_pk_bf16_f32 v3, v6, v7
	v_mov_b32_e32 v6, v5
	v_mad_u64_u32 v[6:7], s[0:1], v17, s90, v[6:7]
	v_mov_b32_e32 v5, v6
	v_cvt_pk_bf16_f32 v0, v8, v9
	v_cvt_pk_bf16_f32 v1, v10, v11
	v_lshl_add_u64 v[4:5], v[136:137], 1, v[4:5]
	s_mov_b64 s[0:1], -1
	global_store_dwordx4 v[4:5], v[0:3], off sc1
	s_cbranch_vccnz .LBB0_1407
	s_andn2_b64 vcc, exec, s[6:7]
	s_cbranch_vccnz .LBB0_1406
	s_barrier
	s_branch .LBB0_1406
